# speedup vs baseline: 1.0104x; 1.0076x over previous
; #define MFMA32(a, b, c) __builtin_amdgcn_mfma_f32_32x32x16_bf16((a), (b), (c), 0, 0, 0)
; DI void gemm_mainloop(const bf16_t* __restrict__ A, int lda, const bf16_t* __restrict__ B, int ldb, int K,
;                       f32x16 (&acc)[2][4], char* smem, const int tid) {
;     ...
;   for (int kt = 0; kt < nk; ++kt) {
;     asm volatile("s_waitcnt vmcnt(8) lgkmcnt(0)" ::: "memory");
;     __builtin_amdgcn_s_barrier();
;     dma_stage(A, lda, B, ldb, (kt + 3) * 32, smem + ((kt + 3) & 3) * STG, w, lane);
;     const char* st = smem + (kt & 3) * STG;
;     _Pragma("unroll") for (int ks = 0; ks < 2; ++ks) {
;       const int oo = ks ? o1 : o0;
;       bf16x8 a0 = *(const bf16x8*)(st + aoff + oo);
;       bf16x8 a1 = *(const bf16x8*)(st + aoff + 32 * 64 + oo);
;       bf16x8 b0 = *(const bf16x8*)(st + boff + oo);
;       bf16x8 b1 = *(const bf16x8*)(st + boff + 32 * 64 + oo);
;       bf16x8 b2 = *(const bf16x8*)(st + boff + 64 * 64 + oo);
;       bf16x8 b3 = *(const bf16x8*)(st + boff + 96 * 64 + oo);
;       acc[0][0] = MFMA32(a0, b0, acc[0][0]); acc[0][1] = MFMA32(a0, b1, acc[0][1]);
;       acc[0][2] = MFMA32(a0, b2, acc[0][2]); acc[0][3] = MFMA32(a0, b3, acc[0][3]);
;       acc[1][0] = MFMA32(a1, b0, acc[1][0]); acc[1][1] = MFMA32(a1, b1, acc[1][1]);
;       acc[1][2] = MFMA32(a1, b2, acc[1][2]); acc[1][3] = MFMA32(a1, b3, acc[1][3]);
;     }
;   }
; DI void rstd_publish(float s, float invK, float* srstd, int tid) {
;   if (tid < 256) srstd[tid] = rsqrtf(s * invK + EPS);
;   __syncthreads();
.Lgm_p1p_loop:
	s_waitcnt lgkmcnt(4)
	v_mfma_f32_32x32x16_bf16 v[112:127], v[166:169], v[174:177], v[112:127]
	v_mfma_f32_32x32x16_bf16 v[96:111], v[166:169], v[178:181], v[96:111]
	v_mfma_f32_32x32x16_bf16 v[48:63], v[166:169], v[182:185], v[48:63]
	v_mfma_f32_32x32x16_bf16 v[32:47], v[166:169], v[186:189], v[32:47]
	v_mfma_f32_32x32x16_bf16 v[80:95], v[170:173], v[174:177], v[80:95]
	v_mfma_f32_32x32x16_bf16 v[64:79], v[170:173], v[178:181], v[64:79]
	v_mfma_f32_32x32x16_bf16 v[16:31], v[170:173], v[182:185], v[16:31]
	v_mfma_f32_32x32x16_bf16 v[0:15], v[170:173], v[186:189], v[0:15]
	s_waitcnt vmcnt(8) lgkmcnt(0)
	s_barrier
	v_mfma_f32_32x32x16_bf16 v[112:127], v[212:215], v[220:223], v[112:127]
	ds_read_b128 v[166:169], v190 offset:32768
	s_mov_b32 m0, s5
	v_lshl_add_u64 v[142:143], v[136:137], 0, s[20:21]
	global_load_lds_dwordx4 v[142:143], off
	v_mfma_f32_32x32x16_bf16 v[96:111], v[212:215], v[224:227], v[96:111]
	ds_read_b128 v[170:173], v190 offset:34816
	s_add_u32 m0, s5, 0x2000
	v_lshl_add_u64 v[148:149], v[130:131], 0, s[20:21]
	global_load_lds_dwordx4 v[148:149], off
	v_mfma_f32_32x32x16_bf16 v[48:63], v[212:215], v[228:231], v[48:63]
	ds_read_b128 v[174:177], v191 offset:49152
	s_add_u32 m0, s5, 0x4000
	v_lshl_add_u64 v[142:143], v[140:141], 0, s[20:21]
	global_load_lds_dwordx4 v[142:143], off
	v_mfma_f32_32x32x16_bf16 v[32:47], v[212:215], v[232:235], v[32:47]
	ds_read_b128 v[178:181], v191 offset:51200
	s_add_u32 m0, s5, 0x6000
	v_lshl_add_u64 v[148:149], v[138:139], 0, s[20:21]
	global_load_lds_dwordx4 v[148:149], off
	ds_read_b128 v[212:215], v132 offset:32768
	s_add_u32 s20, s20, 64
	s_addc_u32 s21, s21, 0
	v_mfma_f32_32x32x16_bf16 v[80:95], v[216:219], v[220:223], v[80:95]
	ds_read_b128 v[182:185], v191 offset:53248
	ds_read_b128 v[220:223], v165 offset:49152
	v_mfma_f32_32x32x16_bf16 v[64:79], v[216:219], v[224:227], v[64:79]
	ds_read_b128 v[186:189], v191 offset:55296
	ds_read_b128 v[224:227], v165 offset:51200
	v_mfma_f32_32x32x16_bf16 v[16:31], v[216:219], v[228:231], v[16:31]
	ds_read_b128 v[228:231], v165 offset:53248
	v_mfma_f32_32x32x16_bf16 v[0:15], v[216:219], v[232:235], v[0:15]
	ds_read_b128 v[232:235], v165 offset:55296
	ds_read_b128 v[216:219], v132 offset:34816
	v_xor_b32_e32 v190, 0x10000, v190
	v_xor_b32_e32 v191, 0x10000, v191
	v_xor_b32_e32 v132, 0x10000, v132
	v_xor_b32_e32 v165, 0x10000, v165
	s_waitcnt lgkmcnt(4)
	v_mfma_f32_32x32x16_bf16 v[112:127], v[166:169], v[174:177], v[112:127]
	v_mfma_f32_32x32x16_bf16 v[96:111], v[166:169], v[178:181], v[96:111]
	v_mfma_f32_32x32x16_bf16 v[48:63], v[166:169], v[182:185], v[48:63]
	v_mfma_f32_32x32x16_bf16 v[32:47], v[166:169], v[186:189], v[32:47]
	v_mfma_f32_32x32x16_bf16 v[80:95], v[170:173], v[174:177], v[80:95]
	v_mfma_f32_32x32x16_bf16 v[64:79], v[170:173], v[178:181], v[64:79]
	v_mfma_f32_32x32x16_bf16 v[16:31], v[170:173], v[182:185], v[16:31]
	v_mfma_f32_32x32x16_bf16 v[0:15], v[170:173], v[186:189], v[0:15]
	s_waitcnt vmcnt(8) lgkmcnt(0)
	s_barrier
	v_mfma_f32_32x32x16_bf16 v[112:127], v[212:215], v[220:223], v[112:127]
	ds_read_b128 v[166:169], v190
	s_add_u32 m0, s5, 0x8000
	v_lshl_add_u64 v[142:143], v[136:137], 0, s[20:21]
	global_load_lds_dwordx4 v[142:143], off
	v_mfma_f32_32x32x16_bf16 v[96:111], v[212:215], v[224:227], v[96:111]
	ds_read_b128 v[170:173], v190 offset:2048
	s_add_u32 m0, s5, 0xa000
	v_lshl_add_u64 v[148:149], v[130:131], 0, s[20:21]
	global_load_lds_dwordx4 v[148:149], off
	v_mfma_f32_32x32x16_bf16 v[48:63], v[212:215], v[228:231], v[48:63]
	ds_read_b128 v[174:177], v191 offset:16384
	s_add_u32 m0, s5, 0xc000
	v_lshl_add_u64 v[142:143], v[140:141], 0, s[20:21]
	global_load_lds_dwordx4 v[142:143], off
	v_mfma_f32_32x32x16_bf16 v[32:47], v[212:215], v[232:235], v[32:47]
	ds_read_b128 v[178:181], v191 offset:18432
	s_add_u32 m0, s5, 0xe000
	v_lshl_add_u64 v[148:149], v[138:139], 0, s[20:21]
	global_load_lds_dwordx4 v[148:149], off
	ds_read_b128 v[212:215], v132
	s_add_u32 s20, s20, 64
	s_addc_u32 s21, s21, 0
	v_mfma_f32_32x32x16_bf16 v[80:95], v[216:219], v[220:223], v[80:95]
	ds_read_b128 v[182:185], v191 offset:20480
	ds_read_b128 v[220:223], v165 offset:16384
	v_mfma_f32_32x32x16_bf16 v[64:79], v[216:219], v[224:227], v[64:79]
	ds_read_b128 v[186:189], v191 offset:22528
	ds_read_b128 v[224:227], v165 offset:18432
	v_mfma_f32_32x32x16_bf16 v[16:31], v[216:219], v[228:231], v[16:31]
	ds_read_b128 v[228:231], v165 offset:20480
	v_mfma_f32_32x32x16_bf16 v[0:15], v[216:219], v[232:235], v[0:15]
	ds_read_b128 v[232:235], v165 offset:22528
	ds_read_b128 v[216:219], v132 offset:2048
	s_xor_b32 s5, s5, 0x10000
	s_add_u32 s2, s2, 0x80
	s_cmpk_lg_i32 s2, 0x1000
	s_cbranch_scc1 .Lgm_p1p_loop
	s_waitcnt lgkmcnt(0)
	s_mov_b64 s[20:21], 0xc0
	s_waitcnt vmcnt(0)
	s_waitcnt vmcnt(0)
	s_barrier
	s_and_saveexec_b64 s[2:3], vcc
	s_cbranch_execz .LBB0_241
	v_mul_f32_e32 v130, 0x4b800000, v135
	v_cmp_gt_f32_e32 vcc, s24, v135
	v_lshl_add_u32 v131, v128, 2, 0
	v_add_u32_e32 v131, 0x12000, v131
	v_cndmask_b32_e32 v130, v135, v130, vcc
	v_rsq_f32_e32 v130, v130
	s_nop 0
	v_mul_f32_e32 v132, 0x45800000, v130
	v_cndmask_b32_e32 v130, v130, v132, vcc
	ds_write_b32 v131, v130

; #define MFMA32(a, b, c) __builtin_amdgcn_mfma_f32_32x32x16_bf16((a), (b), (c), 0, 0, 0)
; DI void gemm_mainloop(const bf16_t* __restrict__ A, int lda, const bf16_t* __restrict__ B, int ldb, int K,
;                       f32x16 (&acc)[2][4], char* smem, const int tid) {
;     ...
;   for (int kt = 0; kt < nk; ++kt) {
;     asm volatile("s_waitcnt vmcnt(8) lgkmcnt(0)" ::: "memory");
;     __builtin_amdgcn_s_barrier();
;     dma_stage(A, lda, B, ldb, (kt + 3) * 32, smem + ((kt + 3) & 3) * STG, w, lane);
;     const char* st = smem + (kt & 3) * STG;
;     _Pragma("unroll") for (int ks = 0; ks < 2; ++ks) {
;       const int oo = ks ? o1 : o0;
;       bf16x8 a0 = *(const bf16x8*)(st + aoff + oo);
;       bf16x8 a1 = *(const bf16x8*)(st + aoff + 32 * 64 + oo);
;       bf16x8 b0 = *(const bf16x8*)(st + boff + oo);
;       bf16x8 b1 = *(const bf16x8*)(st + boff + 32 * 64 + oo);
;       bf16x8 b2 = *(const bf16x8*)(st + boff + 64 * 64 + oo);
;       bf16x8 b3 = *(const bf16x8*)(st + boff + 96 * 64 + oo);
;       acc[0][0] = MFMA32(a0, b0, acc[0][0]); acc[0][1] = MFMA32(a0, b1, acc[0][1]);
;       acc[0][2] = MFMA32(a0, b2, acc[0][2]); acc[0][3] = MFMA32(a0, b3, acc[0][3]);
;       acc[1][0] = MFMA32(a1, b0, acc[1][0]); acc[1][1] = MFMA32(a1, b1, acc[1][1]);
;       acc[1][2] = MFMA32(a1, b2, acc[1][2]); acc[1][3] = MFMA32(a1, b3, acc[1][3]);
;     }
;   }
.Lgm_p5o_loop:
	s_waitcnt lgkmcnt(4)
	v_mfma_f32_32x32x16_bf16 v[112:127], v[170:173], v[178:181], v[112:127]
	v_mfma_f32_32x32x16_bf16 v[96:111], v[170:173], v[182:185], v[96:111]
	v_mfma_f32_32x32x16_bf16 v[48:63], v[170:173], v[186:189], v[48:63]
	v_mfma_f32_32x32x16_bf16 v[32:47], v[170:173], v[190:193], v[32:47]
	v_mfma_f32_32x32x16_bf16 v[80:95], v[174:177], v[178:181], v[80:95]
	v_mfma_f32_32x32x16_bf16 v[64:79], v[174:177], v[182:185], v[64:79]
	v_mfma_f32_32x32x16_bf16 v[16:31], v[174:177], v[186:189], v[16:31]
	v_mfma_f32_32x32x16_bf16 v[0:15], v[174:177], v[190:193], v[0:15]
	s_waitcnt vmcnt(8) lgkmcnt(0)
	s_barrier
	v_mfma_f32_32x32x16_bf16 v[112:127], v[212:215], v[220:223], v[112:127]
	ds_read_b128 v[170:173], v195 offset:32768
	s_mov_b32 m0, s17
	v_lshl_add_u64 v[136:137], v[130:131], 0, s[24:25]
	global_load_lds_dwordx4 v[136:137], off
	v_mfma_f32_32x32x16_bf16 v[96:111], v[212:215], v[224:227], v[96:111]
	ds_read_b128 v[174:177], v195 offset:34816
	s_add_u32 m0, s17, 0x2000
	v_lshl_add_u64 v[138:139], v[128:129], 0, s[24:25]
	global_load_lds_dwordx4 v[138:139], off
	v_mfma_f32_32x32x16_bf16 v[48:63], v[212:215], v[228:231], v[48:63]
	ds_read_b128 v[178:181], v196 offset:49152
	s_add_u32 m0, s17, 0x4000
	v_lshl_add_u64 v[136:137], v[134:135], 0, s[24:25]
	global_load_lds_dwordx4 v[136:137], off
	v_mfma_f32_32x32x16_bf16 v[32:47], v[212:215], v[232:235], v[32:47]
	ds_read_b128 v[182:185], v196 offset:51200
	s_add_u32 m0, s17, 0x6000
	v_lshl_add_u64 v[138:139], v[132:133], 0, s[24:25]
	global_load_lds_dwordx4 v[138:139], off
	ds_read_b128 v[212:215], v152 offset:32768
	s_add_u32 s24, s24, 64
	s_addc_u32 s25, s25, 0
	v_mfma_f32_32x32x16_bf16 v[80:95], v[216:219], v[220:223], v[80:95]
	ds_read_b128 v[186:189], v196 offset:53248
	ds_read_b128 v[220:223], v194 offset:49152
	v_mfma_f32_32x32x16_bf16 v[64:79], v[216:219], v[224:227], v[64:79]
	ds_read_b128 v[190:193], v196 offset:55296
	ds_read_b128 v[224:227], v194 offset:51200
	v_mfma_f32_32x32x16_bf16 v[16:31], v[216:219], v[228:231], v[16:31]
	ds_read_b128 v[228:231], v194 offset:53248
	v_mfma_f32_32x32x16_bf16 v[0:15], v[216:219], v[232:235], v[0:15]
	ds_read_b128 v[232:235], v194 offset:55296
	ds_read_b128 v[216:219], v152 offset:34816
	v_xor_b32_e32 v195, 0x10000, v195
	v_xor_b32_e32 v196, 0x10000, v196
	v_xor_b32_e32 v152, 0x10000, v152
	v_xor_b32_e32 v194, 0x10000, v194
	s_waitcnt lgkmcnt(4)
	v_mfma_f32_32x32x16_bf16 v[112:127], v[170:173], v[178:181], v[112:127]
	v_mfma_f32_32x32x16_bf16 v[96:111], v[170:173], v[182:185], v[96:111]
	v_mfma_f32_32x32x16_bf16 v[48:63], v[170:173], v[186:189], v[48:63]
	v_mfma_f32_32x32x16_bf16 v[32:47], v[170:173], v[190:193], v[32:47]
	v_mfma_f32_32x32x16_bf16 v[80:95], v[174:177], v[178:181], v[80:95]
	v_mfma_f32_32x32x16_bf16 v[64:79], v[174:177], v[182:185], v[64:79]
	v_mfma_f32_32x32x16_bf16 v[16:31], v[174:177], v[186:189], v[16:31]
	v_mfma_f32_32x32x16_bf16 v[0:15], v[174:177], v[190:193], v[0:15]
	s_waitcnt vmcnt(8) lgkmcnt(0)
	s_barrier
	v_mfma_f32_32x32x16_bf16 v[112:127], v[212:215], v[220:223], v[112:127]
	ds_read_b128 v[170:173], v195
	s_add_u32 m0, s17, 0x8000
	v_lshl_add_u64 v[136:137], v[130:131], 0, s[24:25]
	global_load_lds_dwordx4 v[136:137], off
	v_mfma_f32_32x32x16_bf16 v[96:111], v[212:215], v[224:227], v[96:111]
	ds_read_b128 v[174:177], v195 offset:2048
	s_add_u32 m0, s17, 0xa000
	v_lshl_add_u64 v[138:139], v[128:129], 0, s[24:25]
	global_load_lds_dwordx4 v[138:139], off
	v_mfma_f32_32x32x16_bf16 v[48:63], v[212:215], v[228:231], v[48:63]
	ds_read_b128 v[178:181], v196 offset:16384
	s_add_u32 m0, s17, 0xc000
	v_lshl_add_u64 v[136:137], v[134:135], 0, s[24:25]
	global_load_lds_dwordx4 v[136:137], off
	v_mfma_f32_32x32x16_bf16 v[32:47], v[212:215], v[232:235], v[32:47]
	ds_read_b128 v[182:185], v196 offset:18432
	s_add_u32 m0, s17, 0xe000
	v_lshl_add_u64 v[138:139], v[132:133], 0, s[24:25]
	global_load_lds_dwordx4 v[138:139], off
	ds_read_b128 v[212:215], v152
	s_add_u32 s24, s24, 64
	s_addc_u32 s25, s25, 0
	v_mfma_f32_32x32x16_bf16 v[80:95], v[216:219], v[220:223], v[80:95]
	ds_read_b128 v[186:189], v196 offset:20480
	ds_read_b128 v[220:223], v194 offset:16384
	v_mfma_f32_32x32x16_bf16 v[64:79], v[216:219], v[224:227], v[64:79]
	ds_read_b128 v[190:193], v196 offset:22528
	ds_read_b128 v[224:227], v194 offset:18432
	v_mfma_f32_32x32x16_bf16 v[16:31], v[216:219], v[228:231], v[16:31]
	ds_read_b128 v[228:231], v194 offset:20480
	v_mfma_f32_32x32x16_bf16 v[0:15], v[216:219], v[232:235], v[0:15]
	ds_read_b128 v[232:235], v194 offset:22528
	ds_read_b128 v[216:219], v152 offset:2048
	s_xor_b32 s17, s17, 0x10000
	s_add_u32 s2, s2, 0x80
	s_cmpk_lg_i32 s2, 0x1000
	s_cbranch_scc1 .Lgm_p5o_loop
; DI float red8(float s) { s += __shfl_xor(s, 1); s += __shfl_xor(s, 2); s += __shfl_xor(s, 4); return s; }
; DI void p5_tile(const Params& P, int l, int half, int t, char* smem) {
;     ...
;   _Pragma("unroll") for (int seg = 0; seg < 2; ++seg) {
;     const int gc = n0 + wn * 128 + seg * 64 + ch * 8;
;     _Pragma("unroll") for (int mi = 0; mi < 2; ++mi) {
;       stage_block(acc[mi][2 * seg], acc[mi][2 * seg + 1], sE, r, h);
;       _Pragma("unroll") for (int ps = 0; ps < 4; ++ps) {
;         const int rr = ps * 8 + (lane >> 3);
;         const int m = m0 + wm * 64 + mi * 32 + rr;
;         const size_t off = (size_t)m * DM + gc;
;         float v[8]; read8(sE + rr * EST + ch * 8, v);
;         float x[8]; read8(xin + off, x);
;         _Pragma("unroll") for (int j = 0; j < 8; ++j) v[j] += x[j];
;         *(float4*)(xo + off) = make_float4(v[0], v[1], v[2], v[3]);
;         *(float4*)(xo + off + 4) = make_float4(v[4], v[5], v[6], v[7]);
;         if (l < DEPTH - 1) {
;           *(u32x4*)(xbo + off) = pack8u(v);
;           float sq = red8(sum8sq(v));
;           if (ch == 0) sqn[(size_t)m * 32 + ((n0 + wn * 128 + seg * 64) >> 6)] = sq;
;         }
;       }
	s_waitcnt lgkmcnt(0)
	s_mov_b64 s[24:25], 0xc0
	s_movk_i32 s1, 0x2200
	v_mul_lo_u32 v128, v159, s1
	v_mul_u32_u24_e32 v129, 0x110, v158
	v_add_u32_e32 v130, 0, v128
	v_lshlrev_b32_e32 v129, 2, v129
	v_lshlrev_b32_e32 v132, 2, v156
	v_add3_u32 v134, v130, v129, v132
	v_add3_u32 v135, v130, v132, v129
	v_and_b32_e32 v131, 7, v157
	v_lshrrev_b32_e32 v129, 3, v154
	v_add_u32_e32 v143, s0, v155
	v_add_u32_e32 v136, 0x800, v134
	v_add_u32_e32 v137, 0x800, v135
	v_add_u32_e32 v140, 0x1000, v135
	s_waitcnt vmcnt(0)
	s_waitcnt vmcnt(0)
	s_barrier
	v_or_b32_e32 v128, s16, v160
	v_lshlrev_b32_e32 v152, 3, v131
	ds_write2_b32 v134, v112, v113 offset1:68
	ds_write2_b32 v135, v96, v97 offset0:32 offset1:100
	ds_write2_b32 v134, v114, v115 offset0:136 offset1:204
	ds_write2_b32 v135, v98, v99 offset0:168 offset1:236
	ds_write2_b32 v136, v116, v117 offset0:32 offset1:100
	ds_write2_b32 v137, v100, v101 offset0:64 offset1:132
	ds_write2_b32 v136, v118, v119 offset0:168 offset1:236
	ds_write2_b32 v140, v104, v105 offset0:96 offset1:164
	v_or_b32_e32 v104, v143, v129
	v_or_b32_e32 v132, v128, v152
	v_add_u32_e32 v141, 0x1200, v134
	v_ashrrev_i32_e32 v105, 31, v104
	v_ashrrev_i32_e32 v133, 31, v132
	ds_write2_b32 v141, v122, v123 offset0:72 offset1:140
	v_add_u32_e32 v123, 0x1200, v135
	v_add_u32_e32 v142, 0x1800, v134
	v_lshlrev_b64 v[112:113], 11, v[104:105]
	ds_write2_b32 v123, v106, v107 offset0:104 offset1:172
	ds_write2_b32 v142, v124, v125 offset0:96 offset1:164
	v_add_u32_e32 v125, 0x1a00, v134
	v_lshl_add_u64 v[106:107], v[112:113], 0, v[132:133]
	v_lshl_add_u32 v154, v131, 5, v130
	v_add_u32_e32 v138, 0xa00, v135
	v_add_u32_e32 v139, 0x1000, v134
	v_add_u32_e32 v124, 0x1800, v135
	ds_write2_b32 v125, v126, v127 offset0:104 offset1:172
	v_add_u32_e32 v126, 0x1c00, v135
	s_movk_i32 s2, 0x110
	v_lshlrev_b64 v[118:119], 2, v[106:107]
	ds_write2_b32 v138, v102, v103 offset0:72 offset1:140
	ds_write2_b32 v139, v120, v121 offset0:64 offset1:132
	ds_write2_b32 v124, v108, v109 offset0:128 offset1:196
	ds_write2_b32 v126, v110, v111 offset0:8 offset1:76
	v_mad_u32_u24 v102, v129, s2, v154
	v_lshl_add_u64 v[100:101], s[8:9], 0, v[118:119]
	ds_read_b128 v[96:99], v102
	ds_read_b128 v[108:111], v102 offset:16
	global_load_dwordx4 v[114:117], v[100:101], off offset:16
	s_nop 0
	global_load_dwordx4 v[100:103], v[100:101], off
	v_ashrrev_i32_e32 v130, 6, v128
	v_cmp_eq_u32_e64 s[0:1], 0, v131
	v_ashrrev_i32_e32 v131, 31, v130
	v_lshl_add_u64 v[130:131], v[130:131], 2, s[12:13]
	s_andn2_b64 vcc, exec, s[14:15]
	s_waitcnt vmcnt(0) lgkmcnt(1)
	v_pk_add_f32 v[100:101], v[96:97], v[100:101]
	v_pk_add_f32 v[102:103], v[98:99], v[102:103]
	s_waitcnt lgkmcnt(0)
	v_pk_add_f32 v[96:97], v[108:109], v[114:115]
	v_lshl_add_u64 v[108:109], s[6:7], 0, v[118:119]
	v_pk_add_f32 v[98:99], v[110:111], v[116:117]
	global_store_dwordx4 v[108:109], v[100:103], off
	global_store_dwordx4 v[108:109], v[96:99], off offset:16
	v_cndmask_b32_e64 v108, 0, 1, s[14:15]
	v_cmp_ne_u32_e64 s[2:3], 1, v108
	s_cbranch_vccnz .LBB0_666
	v_cvt_pk_bf16_f32 v108, v100, v101
	v_pk_mul_f32 v[100:101], v[100:101], v[100:101]
	v_cvt_pk_bf16_f32 v109, v102, v103
	v_pk_mul_f32 v[102:103], v[102:103], v[102:103]
	v_add_f32_e32 v100, v100, v101
	v_add_f32_e32 v100, v102, v100
	v_cvt_pk_bf16_f32 v110, v96, v97
	v_pk_mul_f32 v[96:97], v[96:97], v[96:97]
	v_add_f32_e32 v100, v103, v100
	v_add_f32_e32 v96, v96, v100
	v_add_f32_e32 v96, v97, v96
	v_xor_b32_e32 v97, 1, v145
	v_cvt_pk_bf16_f32 v111, v98, v99
	v_pk_mul_f32 v[98:99], v[98:99], v[98:99]
	v_cmp_lt_i32_e32 vcc, v97, v198
	v_add_f32_e32 v96, v98, v96
	v_add_f32_e32 v96, v99, v96
	v_cndmask_b32_e32 v97, v145, v97, vcc
	v_lshlrev_b32_e32 v97, 2, v97
	ds_bpermute_b32 v97, v97, v96
	v_lshl_add_u64 v[106:107], v[106:107], 1, s[10:11]
	global_store_dwordx4 v[106:107], v[108:111], off
	s_waitcnt lgkmcnt(0)
	v_add_f32_e32 v96, v96, v97
	v_xor_b32_e32 v97, 2, v145
	v_cmp_lt_i32_e32 vcc, v97, v198
	s_nop 1
	v_cndmask_b32_e32 v97, v145, v97, vcc
	v_lshlrev_b32_e32 v97, 2, v97
	ds_bpermute_b32 v97, v97, v96
	s_waitcnt lgkmcnt(0)
	v_add_f32_e32 v96, v96, v97
	v_xor_b32_e32 v97, 4, v145
	v_cmp_lt_i32_e32 vcc, v97, v198
	s_nop 1
	v_cndmask_b32_e32 v97, v145, v97, vcc
	v_lshlrev_b32_e32 v97, 2, v97
	ds_bpermute_b32 v97, v97, v96
	s_and_saveexec_b64 s[16:17], s[0:1]
	s_cbranch_execz .LBB0_665
	s_waitcnt lgkmcnt(0)
	v_add_f32_e32 v98, v96, v97
	v_lshlrev_b64 v[96:97], 7, v[104:105]
	v_lshl_add_u64 v[96:97], v[130:131], 0, v[96:97]
	global_store_dword v[96:97], v98, off

; #define MFMA32(a, b, c) __builtin_amdgcn_mfma_f32_32x32x16_bf16((a), (b), (c), 0, 0, 0)
; DI float bflo(unsigned p) { return __uint_as_float(p << 16); }
; DI float bfhi(unsigned p) { return __uint_as_float(p & 0xffff0000u); }
; DI void hgrn_out(const Params& P, int l, int item, char* smem) {
;     ...
;     _Pragma("unroll 2") for (int ks = 0; ks < 8; ++ks) {
;       const int dk0 = 16 * ks + 8 * h;
;       u32x4 qraw = *(const u32x4*)(P.hq + (size_t)(t0 + t) * 1024 + head * 128 + dk0);
;       float4 bt0 = *(const float4*)(bs + t * BST + dk0), bt1 = *(const float4*)(bs + t * BST + dk0 + 4);
;       float4 rf0 = *(const float4*)(bs + 32 * BST + dk0), rf1 = *(const float4*)(bs + 32 * BST + dk0 + 4);
;       float q0 = bflo(qraw[0]), q1 = bfhi(qraw[0]), q2 = bflo(qraw[1]), q3 = bfhi(qraw[1]);
;       float q4 = bflo(qraw[2]), q5 = bfhi(qraw[2]), q6 = bflo(qraw[3]), q7 = bfhi(qraw[3]);
;       bf16x8 qref = pack8(q0 * __expf(bt0.x - rf0.x), q1 * __expf(bt0.y - rf0.y), q2 * __expf(bt0.z - rf0.z), q3 * __expf(bt0.w - rf0.w),
;                           q4 * __expf(bt1.x - rf1.x), q5 * __expf(bt1.y - rf1.y), q6 * __expf(bt1.z - rf1.z), q7 * __expf(bt1.w - rf1.w));
;       bf16x8 qint = pack8(q0 * __expf(bt0.x), q1 * __expf(bt0.y), q2 * __expf(bt0.z), q3 * __expf(bt0.w),
;                           q4 * __expf(bt1.x), q5 * __expf(bt1.y), q6 * __expf(bt1.z), q7 * __expf(bt1.w));
;       _Pragma("unroll") for (int st = 0; st < 2; ++st) {
;         const int s_ = 32 * st + r;
;         u32x4 kraw = *(const u32x4*)(kk + (size_t)(t0 + s_) * 1024 + head * 128 + dk0);
;         float4 b0 = *(const float4*)(bs + s_ * BST + dk0), b1 = *(const float4*)(bs + s_ * BST + dk0 + 4);
;         bf16x8 kt = pack8(bflo(kraw[0]) * __expf(rf0.x - b0.x), bfhi(kraw[0]) * __expf(rf0.y - b0.y),
;                           bflo(kraw[1]) * __expf(rf0.z - b0.z), bfhi(kraw[1]) * __expf(rf0.w - b0.w),
;                           bflo(kraw[2]) * __expf(rf1.x - b1.x), bfhi(kraw[2]) * __expf(rf1.y - b1.y),
;                           bflo(kraw[3]) * __expf(rf1.z - b1.z), bfhi(kraw[3]) * __expf(rf1.w - b1.w));
;         sc[st] = MFMA32(kt, qref, sc[st]);
;       }
.LBB0_743:
	v_lshl_add_u64 v[226:227], v[116:117], 0, s[76:77]
	v_lshl_add_u64 v[230:231], v[122:123], 0, s[76:77]
	v_lshl_add_u64 v[234:235], v[120:121], 0, s[76:77]
	v_lshl_add_u64 v[238:239], v[118:119], 0, s[76:77]
	global_load_dwordx4 v[206:209], v[226:227], off
	global_load_dwordx4 v[210:213], v[230:231], off
	global_load_dwordx4 v[214:217], v[234:235], off
	global_load_dwordx4 v[218:221], v[238:239], off
	v_add_co_u32_e32 v242, vcc, s33, v238
	s_nop 1
	v_addc_co_u32_e32 v243, vcc, 0, v239, vcc
	global_load_dwordx4 v[222:225], v[242:243], off
	global_load_dwordx4 v[226:229], v[226:227], off offset:32
	global_load_dwordx4 v[230:233], v[230:231], off offset:32
	global_load_dwordx4 v[234:237], v[234:235], off offset:32
	global_load_dwordx4 v[238:241], v[238:239], off offset:32
	global_load_dwordx4 v[242:245], v[242:243], off offset:32
	v_lshl_add_u64 v[132:133], v[116:117], 0, s[76:77]
	v_add_u32_e32 v156, v154, v139
	ds_read_b128 v[76:79], v156
	ds_read_b128 v[124:127], v156 offset:16
	ds_read_b128 v[72:75], v154 offset:16896
	ds_read_b128 v[68:71], v154 offset:16912
	s_waitcnt lgkmcnt(1)
	v_sub_f32_e32 v128, v76, v72
	v_sub_f32_e32 v129, v77, v73
	v_sub_f32_e32 v130, v78, v74
	v_sub_f32_e32 v131, v79, v75
	v_mul_f32_e32 v128, 0x3fb8aa3b, v128
	v_mul_f32_e32 v129, 0x3fb8aa3b, v129
	v_mul_f32_e32 v130, 0x3fb8aa3b, v130
	v_mul_f32_e32 v131, 0x3fb8aa3b, v131
	v_exp_f32_e32 v128, v128
	v_exp_f32_e32 v129, v129
	v_exp_f32_e32 v130, v130
	v_exp_f32_e32 v131, v131
	s_waitcnt lgkmcnt(0)
	v_sub_f32_e32 v155, v124, v68
	v_mul_f32_e32 v76, 0x3fb8aa3b, v76
	v_mul_f32_e32 v155, 0x3fb8aa3b, v155
	v_exp_f32_e32 v162, v76
	v_mul_f32_e32 v76, 0x3fb8aa3b, v77
	v_exp_f32_e32 v158, v155
	v_sub_f32_e32 v155, v125, v69
	v_exp_f32_e32 v163, v76
	v_mul_f32_e32 v155, 0x3fb8aa3b, v155
	v_exp_f32_e32 v159, v155
	v_sub_f32_e32 v155, v126, v70
	v_mul_f32_e32 v155, 0x3fb8aa3b, v155
	v_exp_f32_e32 v160, v155
	v_sub_f32_e32 v155, v127, v71
	v_mul_f32_e32 v155, 0x3fb8aa3b, v155
	v_exp_f32_e32 v161, v155
	v_add_u32_e32 v155, v154, v142
	s_waitcnt vmcnt(9)
	v_lshlrev_b32_e32 v164, 16, v206
	v_and_b32_e32 v165, 0xffff0000, v206
	v_mul_f32_e32 v64, 0x3fb8aa3b, v78
	v_exp_f32_e32 v78, v64
	v_mul_f32_e32 v64, 0x3fb8aa3b, v79
	v_exp_f32_e32 v79, v64
	v_lshlrev_b32_e32 v64, 16, v207
	v_and_b32_e32 v65, 0xffff0000, v207
	v_mul_f32_e32 v76, v128, v164
	v_mul_f32_e32 v77, v129, v165
	v_mul_f32_e32 v130, v130, v64
	v_mul_f32_e32 v131, v131, v65
	v_cvt_pk_bf16_f32 v76, v76, v77
	v_cvt_pk_bf16_f32 v77, v130, v131
	v_mul_f32_e32 v130, v78, v64
	v_mul_f32_e32 v131, v79, v65
	v_mul_f32_e32 v64, 0x3fb8aa3b, v124
	v_mul_f32_e32 v65, 0x3fb8aa3b, v125
	v_exp_f32_e32 v64, v64
	v_exp_f32_e32 v65, v65
	v_lshlrev_b32_e32 v124, 16, v208
	v_and_b32_e32 v125, 0xffff0000, v208
	v_mul_f32_e32 v78, v158, v124
	v_mul_f32_e32 v79, v159, v125
	v_mul_f32_e32 v124, v64, v124
	v_mul_f32_e32 v125, v65, v125
	v_mul_f32_e32 v64, 0x3fb8aa3b, v126
	v_mul_f32_e32 v65, 0x3fb8aa3b, v127
	v_exp_f32_e32 v64, v64
	v_exp_f32_e32 v65, v65
	v_lshlrev_b32_e32 v66, 16, v209
	v_and_b32_e32 v67, 0xffff0000, v209
	v_mul_f32_e32 v126, v160, v66
	v_mul_f32_e32 v127, v161, v67
	v_mul_f32_e32 v128, v162, v164
	v_mul_f32_e32 v129, v163, v165
	v_cvt_pk_bf16_f32 v78, v78, v79
	v_cvt_pk_bf16_f32 v79, v126, v127
	v_mul_f32_e32 v126, v64, v66
	v_mul_f32_e32 v127, v65, v67
	v_cvt_pk_bf16_f32 v66, v124, v125
	v_lshl_add_u64 v[124:125], v[122:123], 0, s[76:77]
	v_cvt_pk_bf16_f32 v64, v128, v129
	v_cvt_pk_bf16_f32 v67, v126, v127
	ds_read_b128 v[158:161], v155
	ds_read_b128 v[162:165], v155 offset:16
	v_cvt_pk_bf16_f32 v65, v130, v131
	s_waitcnt lgkmcnt(1)
	v_sub_f32_e32 v130, v72, v158
	v_sub_f32_e32 v131, v73, v159
	v_mul_f32_e32 v130, 0x3fb8aa3b, v130
	v_mul_f32_e32 v131, 0x3fb8aa3b, v131
	v_exp_f32_e32 v130, v130
	v_exp_f32_e32 v131, v131
	s_waitcnt vmcnt(8)
	v_lshlrev_b32_e32 v158, 16, v210
	v_and_b32_e32 v159, 0xffff0000, v210
	v_sub_f32_e32 v126, v74, v160
	v_mul_f32_e32 v126, 0x3fb8aa3b, v126
	v_mul_f32_e32 v130, v130, v158
	v_mul_f32_e32 v131, v131, v159
	v_exp_f32_e32 v158, v126
	v_sub_f32_e32 v126, v75, v161
	v_mul_f32_e32 v126, 0x3fb8aa3b, v126
	v_exp_f32_e32 v159, v126
	v_lshlrev_b32_e32 v126, 16, v211
	v_and_b32_e32 v127, 0xffff0000, v211
	v_lshlrev_b32_e32 v160, 16, v212
	v_mul_f32_e32 v158, v158, v126
	v_mul_f32_e32 v159, v159, v127
	s_waitcnt lgkmcnt(0)
	v_sub_f32_e32 v126, v68, v162
	v_sub_f32_e32 v127, v69, v163
	v_mul_f32_e32 v126, 0x3fb8aa3b, v126
	v_mul_f32_e32 v127, 0x3fb8aa3b, v127
	v_exp_f32_e32 v126, v126
	v_exp_f32_e32 v127, v127
	v_and_b32_e32 v161, 0xffff0000, v212
	v_lshlrev_b32_e32 v128, 16, v213
	v_and_b32_e32 v129, 0xffff0000, v213
	v_mul_f32_e32 v160, v126, v160
	v_mul_f32_e32 v161, v127, v161
	v_sub_f32_e32 v126, v70, v164
	v_sub_f32_e32 v127, v71, v165
	v_mul_f32_e32 v126, 0x3fb8aa3b, v126
	v_mul_f32_e32 v127, 0x3fb8aa3b, v127
	v_exp_f32_e32 v126, v126
	v_exp_f32_e32 v127, v127
	s_nop 0
	v_mul_f32_e32 v162, v126, v128
	v_mul_f32_e32 v163, v127, v129
	v_cvt_pk_bf16_f32 v126, v130, v131
	v_cvt_pk_bf16_f32 v127, v158, v159
	v_cvt_pk_bf16_f32 v128, v160, v161
	v_cvt_pk_bf16_f32 v129, v162, v163
	s_nop 1
	v_mfma_f32_32x32x16_bf16 v[48:63], v[126:129], v[76:79], v[48:63]
	v_lshl_add_u64 v[126:127], v[120:121], 0, s[76:77]
	ds_read_b128 v[158:161], v155 offset:16896
	ds_read_b128 v[162:165], v155 offset:16912
	s_waitcnt lgkmcnt(1)
	v_sub_f32_e32 v74, v74, v160
	v_sub_f32_e32 v75, v75, v161
	v_mul_f32_e32 v74, 0x3fb8aa3b, v74
	v_mul_f32_e32 v75, 0x3fb8aa3b, v75
	s_waitcnt lgkmcnt(0)
; #define MFMA32(a, b, c) __builtin_amdgcn_mfma_f32_32x32x16_bf16((a), (b), (c), 0, 0, 0)
; DI float bflo(unsigned p) { return __uint_as_float(p << 16); }
; DI float bfhi(unsigned p) { return __uint_as_float(p & 0xffff0000u); }
; DI void hgrn_out(const Params& P, int l, int item, char* smem) {
;     ...
;     _Pragma("unroll 2") for (int ks = 0; ks < 8; ++ks) {
;       const int dk0 = 16 * ks + 8 * h;
;       u32x4 qraw = *(const u32x4*)(P.hq + (size_t)(t0 + t) * 1024 + head * 128 + dk0);
;       float4 bt0 = *(const float4*)(bs + t * BST + dk0), bt1 = *(const float4*)(bs + t * BST + dk0 + 4);
;       float4 rf0 = *(const float4*)(bs + 32 * BST + dk0), rf1 = *(const float4*)(bs + 32 * BST + dk0 + 4);
;       float q0 = bflo(qraw[0]), q1 = bfhi(qraw[0]), q2 = bflo(qraw[1]), q3 = bfhi(qraw[1]);
;       float q4 = bflo(qraw[2]), q5 = bfhi(qraw[2]), q6 = bflo(qraw[3]), q7 = bfhi(qraw[3]);
;       bf16x8 qref = pack8(q0 * __expf(bt0.x - rf0.x), q1 * __expf(bt0.y - rf0.y), q2 * __expf(bt0.z - rf0.z), q3 * __expf(bt0.w - rf0.w),
;                           q4 * __expf(bt1.x - rf1.x), q5 * __expf(bt1.y - rf1.y), q6 * __expf(bt1.z - rf1.z), q7 * __expf(bt1.w - rf1.w));
;       bf16x8 qint = pack8(q0 * __expf(bt0.x), q1 * __expf(bt0.y), q2 * __expf(bt0.z), q3 * __expf(bt0.w),
;                           q4 * __expf(bt1.x), q5 * __expf(bt1.y), q6 * __expf(bt1.z), q7 * __expf(bt1.w));
;       _Pragma("unroll") for (int st = 0; st < 2; ++st) {
;         const int s_ = 32 * st + r;
;         u32x4 kraw = *(const u32x4*)(kk + (size_t)(t0 + s_) * 1024 + head * 128 + dk0);
;         float4 b0 = *(const float4*)(bs + s_ * BST + dk0), b1 = *(const float4*)(bs + s_ * BST + dk0 + 4);
;         bf16x8 kt = pack8(bflo(kraw[0]) * __expf(rf0.x - b0.x), bfhi(kraw[0]) * __expf(rf0.y - b0.y),
;                           bflo(kraw[1]) * __expf(rf0.z - b0.z), bfhi(kraw[1]) * __expf(rf0.w - b0.w),
;                           bflo(kraw[2]) * __expf(rf1.x - b1.x), bfhi(kraw[2]) * __expf(rf1.y - b1.y),
;                           bflo(kraw[3]) * __expf(rf1.z - b1.z), bfhi(kraw[3]) * __expf(rf1.w - b1.w));
;         sc[st] = MFMA32(kt, qref, sc[st]);
;       }
;       _Pragma("unroll") for (int mi = 0; mi < 2; ++mi) {
;         const int dv = 32 * (2 * dh + mi) + r;
;         bf16x8 sfr = *(const bf16x8*)(stp + dv * 128 + dk0);
;         o[mi] = MFMA32(sfr, qint, o[mi]);
;       }
	v_sub_f32_e32 v68, v68, v162
	v_sub_f32_e32 v69, v69, v163
	v_exp_f32_e32 v74, v74
	v_exp_f32_e32 v75, v75
	v_mul_f32_e32 v68, 0x3fb8aa3b, v68
	v_mul_f32_e32 v69, 0x3fb8aa3b, v69
	v_exp_f32_e32 v68, v68
	v_exp_f32_e32 v69, v69
	v_sub_f32_e32 v72, v72, v158
	v_sub_f32_e32 v73, v73, v159
	v_mul_f32_e32 v72, 0x3fb8aa3b, v72
	v_mul_f32_e32 v73, 0x3fb8aa3b, v73
	v_exp_f32_e32 v72, v72
	v_exp_f32_e32 v73, v73
	s_waitcnt vmcnt(7)
	v_lshlrev_b32_e32 v158, 16, v214
	v_and_b32_e32 v159, 0xffff0000, v214
	v_lshlrev_b32_e32 v128, 16, v215
	v_and_b32_e32 v129, 0xffff0000, v215
	v_mul_f32_e32 v74, v74, v128
	v_mul_f32_e32 v75, v75, v129
	v_lshlrev_b32_e32 v128, 16, v216
	v_and_b32_e32 v129, 0xffff0000, v216
	v_mul_f32_e32 v128, v68, v128
	v_mul_f32_e32 v129, v69, v129
	v_sub_f32_e32 v68, v70, v164
	v_sub_f32_e32 v69, v71, v165
	v_mul_f32_e32 v68, 0x3fb8aa3b, v68
	v_mul_f32_e32 v69, 0x3fb8aa3b, v69
	v_exp_f32_e32 v68, v68
	v_exp_f32_e32 v69, v69
	v_lshlrev_b32_e32 v70, 16, v217
	v_and_b32_e32 v71, 0xffff0000, v217
	v_mul_f32_e32 v72, v72, v158
	v_mul_f32_e32 v73, v73, v159
	v_mul_f32_e32 v130, v68, v70
	v_mul_f32_e32 v131, v69, v71
	v_cvt_pk_bf16_f32 v68, v72, v73
	v_cvt_pk_bf16_f32 v69, v74, v75
	v_cvt_pk_bf16_f32 v70, v128, v129
	v_cvt_pk_bf16_f32 v71, v130, v131
	v_lshl_add_u64 v[130:131], v[118:119], 0, s[76:77]
	v_add_co_u32_e32 v128, vcc, s33, v130
	v_mfma_f32_32x32x16_bf16 v[32:47], v[68:71], v[76:79], v[32:47]
	v_addc_co_u32_e32 v129, vcc, 0, v131, vcc
	s_add_u32 s76, s76, 64
	s_addc_u32 s77, s77, 0
	s_cmpk_eq_i32 s76, 0x100
	s_waitcnt vmcnt(6)
	v_mfma_f32_32x32x16_bf16 v[16:31], v[218:221], v[64:67], v[16:31]
	s_waitcnt vmcnt(5)
	v_mfma_f32_32x32x16_bf16 v[0:15], v[222:225], v[64:67], v[0:15]
	ds_read_b128 v[76:79], v156 offset:64
	ds_read_b128 v[156:159], v156 offset:80
	ds_read_b128 v[72:75], v154 offset:16960
	ds_read_b128 v[68:71], v154 offset:16976
	v_add_u32_e32 v154, 0x80, v154
	s_waitcnt lgkmcnt(1)
	v_sub_f32_e32 v132, v76, v72
	v_sub_f32_e32 v133, v77, v73
	v_sub_f32_e32 v160, v78, v74
	v_sub_f32_e32 v161, v79, v75
	v_mul_f32_e32 v132, 0x3fb8aa3b, v132
	v_mul_f32_e32 v133, 0x3fb8aa3b, v133
	v_mul_f32_e32 v160, 0x3fb8aa3b, v160
	v_mul_f32_e32 v161, 0x3fb8aa3b, v161
	v_exp_f32_e32 v132, v132
	v_exp_f32_e32 v133, v133
	v_exp_f32_e32 v160, v160
	v_exp_f32_e32 v161, v161
	v_mul_f32_e32 v76, 0x3fb8aa3b, v76
	v_exp_f32_e32 v166, v76
	v_mul_f32_e32 v76, 0x3fb8aa3b, v77
	s_waitcnt lgkmcnt(0)
	v_sub_f32_e32 v162, v156, v68
	v_sub_f32_e32 v163, v157, v69
	v_exp_f32_e32 v167, v76
	v_mul_f32_e32 v162, 0x3fb8aa3b, v162
	v_mul_f32_e32 v163, 0x3fb8aa3b, v163
	v_exp_f32_e32 v162, v162
	v_exp_f32_e32 v163, v163
	v_sub_f32_e32 v164, v158, v70
	v_sub_f32_e32 v165, v159, v71
	v_mul_f32_e32 v164, 0x3fb8aa3b, v164
	v_mul_f32_e32 v165, 0x3fb8aa3b, v165
	v_exp_f32_e32 v164, v164
	v_exp_f32_e32 v165, v165
	s_waitcnt vmcnt(4)
	v_lshlrev_b32_e32 v168, 16, v226
	v_and_b32_e32 v169, 0xffff0000, v226
	v_mul_f32_e32 v64, 0x3fb8aa3b, v78
	v_exp_f32_e32 v78, v64
	v_mul_f32_e32 v64, 0x3fb8aa3b, v79
	v_exp_f32_e32 v79, v64
	v_lshlrev_b32_e32 v64, 16, v227
	v_and_b32_e32 v65, 0xffff0000, v227
	v_mul_f32_e32 v76, v132, v168
	v_mul_f32_e32 v77, v133, v169
	v_mul_f32_e32 v160, v160, v64
	v_mul_f32_e32 v161, v161, v65
	v_cvt_pk_bf16_f32 v76, v76, v77
	v_cvt_pk_bf16_f32 v77, v160, v161
	v_mul_f32_e32 v160, v78, v64
	v_mul_f32_e32 v161, v79, v65
	v_mul_f32_e32 v64, 0x3fb8aa3b, v156
	v_mul_f32_e32 v65, 0x3fb8aa3b, v157
	v_exp_f32_e32 v64, v64
	v_exp_f32_e32 v65, v65
	v_lshlrev_b32_e32 v156, 16, v228
	v_and_b32_e32 v157, 0xffff0000, v228
	v_mul_f32_e32 v78, v162, v156
	v_mul_f32_e32 v79, v163, v157
	v_mul_f32_e32 v156, v64, v156
	v_mul_f32_e32 v157, v65, v157
	v_mul_f32_e32 v64, 0x3fb8aa3b, v158
	v_mul_f32_e32 v65, 0x3fb8aa3b, v159
	v_exp_f32_e32 v64, v64
	v_exp_f32_e32 v65, v65
	v_lshlrev_b32_e32 v66, 16, v229
	v_and_b32_e32 v67, 0xffff0000, v229
	v_mul_f32_e32 v158, v164, v66
	v_mul_f32_e32 v159, v165, v67
	v_cvt_pk_bf16_f32 v78, v78, v79
	v_cvt_pk_bf16_f32 v79, v158, v159
	v_mul_f32_e32 v158, v64, v66
	v_mul_f32_e32 v159, v65, v67
	v_cvt_pk_bf16_f32 v66, v156, v157
	v_cvt_pk_bf16_f32 v67, v158, v159
	v_mul_f32_e32 v132, v166, v168
	v_mul_f32_e32 v133, v167, v169
	v_cvt_pk_bf16_f32 v65, v160, v161
	ds_read_b128 v[160:163], v155 offset:64
	ds_read_b128 v[164:167], v155 offset:80
	v_cvt_pk_bf16_f32 v64, v132, v133
	s_waitcnt lgkmcnt(1)
; DI void hgrn_out(const Params& P, int l, int item, char* smem) {
;     ...
;     _Pragma("unroll 2") for (int ks = 0; ks < 8; ++ks) {
;       const int dk0 = 16 * ks + 8 * h;
;       u32x4 qraw = *(const u32x4*)(P.hq + (size_t)(t0 + t) * 1024 + head * 128 + dk0);
;       float4 bt0 = *(const float4*)(bs + t * BST + dk0), bt1 = *(const float4*)(bs + t * BST + dk0 + 4);
;       float4 rf0 = *(const float4*)(bs + 32 * BST + dk0), rf1 = *(const float4*)(bs + 32 * BST + dk0 + 4);
;       float q0 = bflo(qraw[0]), q1 = bfhi(qraw[0]), q2 = bflo(qraw[1]), q3 = bfhi(qraw[1]);
;       float q4 = bflo(qraw[2]), q5 = bfhi(qraw[2]), q6 = bflo(qraw[3]), q7 = bfhi(qraw[3]);
;       bf16x8 qref = pack8(q0 * __expf(bt0.x - rf0.x), q1 * __expf(bt0.y - rf0.y), q2 * __expf(bt0.z - rf0.z), q3 * __expf(bt0.w - rf0.w),
;                           q4 * __expf(bt1.x - rf1.x), q5 * __expf(bt1.y - rf1.y), q6 * __expf(bt1.z - rf1.z), q7 * __expf(bt1.w - rf1.w));
;       bf16x8 qint = pack8(q0 * __expf(bt0.x), q1 * __expf(bt0.y), q2 * __expf(bt0.z), q3 * __expf(bt0.w),
;                           q4 * __expf(bt1.x), q5 * __expf(bt1.y), q6 * __expf(bt1.z), q7 * __expf(bt1.w));
;       _Pragma("unroll") for (int st = 0; st < 2; ++st) {
;         const int s_ = 32 * st + r;
;         u32x4 kraw = *(const u32x4*)(kk + (size_t)(t0 + s_) * 1024 + head * 128 + dk0);
;         float4 b0 = *(const float4*)(bs + s_ * BST + dk0), b1 = *(const float4*)(bs + s_ * BST + dk0 + 4);
;         bf16x8 kt = pack8(bflo(kraw[0]) * __expf(rf0.x - b0.x), bfhi(kraw[0]) * __expf(rf0.y - b0.y),
;                           bflo(kraw[1]) * __expf(rf0.z - b0.z), bfhi(kraw[1]) * __expf(rf0.w - b0.w),
;                           bflo(kraw[2]) * __expf(rf1.x - b1.x), bfhi(kraw[2]) * __expf(rf1.y - b1.y),
;                           bflo(kraw[3]) * __expf(rf1.z - b1.z), bfhi(kraw[3]) * __expf(rf1.w - b1.w));
;         sc[st] = MFMA32(kt, qref, sc[st]);
;       }
;       _Pragma("unroll") for (int mi = 0; mi < 2; ++mi) {
;         const int dv = 32 * (2 * dh + mi) + r;
;         bf16x8 sfr = *(const bf16x8*)(stp + dv * 128 + dk0);
;         o[mi] = MFMA32(sfr, qint, o[mi]);
;       }
;     ...
;     _Pragma("unroll") for (int st = 0; st < 2; ++st) {
;       _Pragma("unroll") for (int s2 = 0; s2 < 2; ++s2) {
;         bf16x8 pb = pack8(sc[st][8 * s2], sc[st][8 * s2 + 1], sc[st][8 * s2 + 2], sc[st][8 * s2 + 3],
	v_sub_f32_e32 v124, v72, v160
	v_sub_f32_e32 v125, v73, v161
	v_mul_f32_e32 v124, 0x3fb8aa3b, v124
	v_mul_f32_e32 v125, 0x3fb8aa3b, v125
	v_exp_f32_e32 v124, v124
	v_exp_f32_e32 v125, v125
	s_waitcnt vmcnt(3)
	v_lshlrev_b32_e32 v132, 16, v230
	v_and_b32_e32 v133, 0xffff0000, v230
	v_mul_f32_e32 v124, v124, v132
	v_mul_f32_e32 v125, v125, v133
	v_sub_f32_e32 v132, v74, v162
	v_sub_f32_e32 v133, v75, v163
	v_mul_f32_e32 v132, 0x3fb8aa3b, v132
	v_mul_f32_e32 v133, 0x3fb8aa3b, v133
	v_exp_f32_e32 v132, v132
	v_exp_f32_e32 v133, v133
	v_lshlrev_b32_e32 v156, 16, v231
	v_and_b32_e32 v157, 0xffff0000, v231
	v_lshlrev_b32_e32 v160, 16, v232
	v_mul_f32_e32 v132, v132, v156
	v_mul_f32_e32 v133, v133, v157
	s_waitcnt lgkmcnt(0)
	v_sub_f32_e32 v156, v68, v164
	v_sub_f32_e32 v157, v69, v165
	v_mul_f32_e32 v156, 0x3fb8aa3b, v156
	v_mul_f32_e32 v157, 0x3fb8aa3b, v157
	v_exp_f32_e32 v156, v156
	v_exp_f32_e32 v157, v157
	v_and_b32_e32 v161, 0xffff0000, v232
	v_lshlrev_b32_e32 v158, 16, v233
	v_and_b32_e32 v159, 0xffff0000, v233
	v_mul_f32_e32 v160, v156, v160
	v_mul_f32_e32 v161, v157, v161
	v_sub_f32_e32 v156, v70, v166
	v_sub_f32_e32 v157, v71, v167
	v_mul_f32_e32 v156, 0x3fb8aa3b, v156
	v_mul_f32_e32 v157, 0x3fb8aa3b, v157
	v_exp_f32_e32 v156, v156
	v_exp_f32_e32 v157, v157
	s_nop 0
	v_mul_f32_e32 v162, v156, v158
	v_mul_f32_e32 v163, v157, v159
	v_cvt_pk_bf16_f32 v156, v124, v125
	v_cvt_pk_bf16_f32 v157, v132, v133
	v_cvt_pk_bf16_f32 v158, v160, v161
	v_cvt_pk_bf16_f32 v159, v162, v163
	s_waitcnt vmcnt(2)
	v_lshlrev_b32_e32 v132, 16, v234
	v_mfma_f32_32x32x16_bf16 v[48:63], v[156:159], v[76:79], v[48:63]
	ds_read_b128 v[156:159], v155 offset:16960
	ds_read_b128 v[160:163], v155 offset:16976
	v_and_b32_e32 v133, 0xffff0000, v234
	v_lshlrev_b32_e32 v124, 16, v235
	v_and_b32_e32 v125, 0xffff0000, v235
	s_waitcnt lgkmcnt(1)
	v_sub_f32_e32 v74, v74, v158
	v_sub_f32_e32 v75, v75, v159
	v_mul_f32_e32 v74, 0x3fb8aa3b, v74
	v_mul_f32_e32 v75, 0x3fb8aa3b, v75
	s_waitcnt lgkmcnt(0)
	v_sub_f32_e32 v68, v68, v160
	v_sub_f32_e32 v69, v69, v161
	v_exp_f32_e32 v74, v74
	v_exp_f32_e32 v75, v75
	v_mul_f32_e32 v68, 0x3fb8aa3b, v68
	v_mul_f32_e32 v69, 0x3fb8aa3b, v69
	v_exp_f32_e32 v68, v68
	v_exp_f32_e32 v69, v69
	v_mul_f32_e32 v74, v74, v124
	v_mul_f32_e32 v75, v75, v125
	v_lshlrev_b32_e32 v124, 16, v236
	v_and_b32_e32 v125, 0xffff0000, v236
	v_sub_f32_e32 v72, v72, v156
	v_sub_f32_e32 v73, v73, v157
	v_mul_f32_e32 v124, v68, v124
	v_mul_f32_e32 v125, v69, v125
	v_sub_f32_e32 v68, v70, v162
	v_sub_f32_e32 v69, v71, v163
	v_mul_f32_e32 v72, 0x3fb8aa3b, v72
	v_mul_f32_e32 v73, 0x3fb8aa3b, v73
	v_mul_f32_e32 v68, 0x3fb8aa3b, v68
	v_mul_f32_e32 v69, 0x3fb8aa3b, v69
	v_exp_f32_e32 v72, v72
	v_exp_f32_e32 v73, v73
	v_exp_f32_e32 v68, v68
	v_exp_f32_e32 v69, v69
	v_lshlrev_b32_e32 v70, 16, v237
	v_and_b32_e32 v71, 0xffff0000, v237
	v_mul_f32_e32 v72, v72, v132
	v_mul_f32_e32 v73, v73, v133
	v_mul_f32_e32 v126, v68, v70
	v_mul_f32_e32 v127, v69, v71
	v_cvt_pk_bf16_f32 v68, v72, v73
	v_cvt_pk_bf16_f32 v69, v74, v75
	v_cvt_pk_bf16_f32 v70, v124, v125
	v_cvt_pk_bf16_f32 v71, v126, v127
	s_nop 1
	v_mfma_f32_32x32x16_bf16 v[32:47], v[68:71], v[76:79], v[32:47]
	s_waitcnt vmcnt(1)
	v_mfma_f32_32x32x16_bf16 v[16:31], v[238:241], v[64:67], v[16:31]
	s_waitcnt vmcnt(0)
	v_mfma_f32_32x32x16_bf16 v[0:15], v[242:245], v[64:67], v[0:15]
	s_cbranch_scc0 .LBB0_743
	s_cmp_lg_u32 s98, 0
	s_cbranch_scc1 .Lhout_vloaded
	global_load_dwordx2 v[170:171], v[86:87], off
	global_load_dwordx2 v[172:173], v[86:87], off offset:16
	global_load_dwordx2 v[174:175], v[88:89], off
	global_load_dwordx2 v[176:177], v[88:89], off offset:16
	global_load_dwordx2 v[178:179], v[86:87], off offset:32
	global_load_dwordx2 v[180:181], v[86:87], off offset:48
	global_load_dwordx2 v[182:183], v[90:91], off
	global_load_dwordx2 v[184:185], v[90:91], off offset:16
	global_load_dwordx2 v[186:187], v[86:87], off offset:64
	global_load_dwordx2 v[188:189], v[86:87], off offset:80
	global_load_dwordx2 v[190:191], v[92:93], off
	global_load_dwordx2 v[192:193], v[92:93], off offset:16
	global_load_dwordx2 v[194:195], v[86:87], off offset:96
	global_load_dwordx2 v[196:197], v[86:87], off offset:112
	global_load_dwordx2 v[252:253], v[94:95], off
	global_load_dwordx2 v[254:255], v[94:95], off offset:16
	s_mov_b32 s98, 1

; #define MFMA32(a, b, c) __builtin_amdgcn_mfma_f32_32x32x16_bf16((a), (b), (c), 0, 0, 0)
; DI void gemm_mainloop(const bf16_t* __restrict__ A, int lda, const bf16_t* __restrict__ B, int ldb, int K,
;                       f32x16 (&acc)[2][4], char* smem, const int tid) {
;     ...
;   for (int kt = 0; kt < nk; ++kt) {
;     asm volatile("s_waitcnt vmcnt(8) lgkmcnt(0)" ::: "memory");
;     __builtin_amdgcn_s_barrier();
;     dma_stage(A, lda, B, ldb, (kt + 3) * 32, smem + ((kt + 3) & 3) * STG, w, lane);
;     const char* st = smem + (kt & 3) * STG;
;     _Pragma("unroll") for (int ks = 0; ks < 2; ++ks) {
;       const int oo = ks ? o1 : o0;
;       bf16x8 a0 = *(const bf16x8*)(st + aoff + oo);
;       bf16x8 a1 = *(const bf16x8*)(st + aoff + 32 * 64 + oo);
;       bf16x8 b0 = *(const bf16x8*)(st + boff + oo);
;       bf16x8 b1 = *(const bf16x8*)(st + boff + 32 * 64 + oo);
;       bf16x8 b2 = *(const bf16x8*)(st + boff + 64 * 64 + oo);
;       bf16x8 b3 = *(const bf16x8*)(st + boff + 96 * 64 + oo);
;       acc[0][0] = MFMA32(a0, b0, acc[0][0]); acc[0][1] = MFMA32(a0, b1, acc[0][1]);
;       acc[0][2] = MFMA32(a0, b2, acc[0][2]); acc[0][3] = MFMA32(a0, b3, acc[0][3]);
;       acc[1][0] = MFMA32(a1, b0, acc[1][0]); acc[1][1] = MFMA32(a1, b1, acc[1][1]);
;       acc[1][2] = MFMA32(a1, b2, acc[1][2]); acc[1][3] = MFMA32(a1, b3, acc[1][3]);
;     }
;   }
.Lgm_p5e_loop:
	s_waitcnt lgkmcnt(4)
	v_mfma_f32_32x32x16_bf16 v[112:127], v[170:173], v[178:181], v[112:127]
	v_mfma_f32_32x32x16_bf16 v[96:111], v[170:173], v[182:185], v[96:111]
	v_mfma_f32_32x32x16_bf16 v[48:63], v[170:173], v[186:189], v[48:63]
	v_mfma_f32_32x32x16_bf16 v[32:47], v[170:173], v[190:193], v[32:47]
	v_mfma_f32_32x32x16_bf16 v[80:95], v[174:177], v[178:181], v[80:95]
	v_mfma_f32_32x32x16_bf16 v[64:79], v[174:177], v[182:185], v[64:79]
	v_mfma_f32_32x32x16_bf16 v[16:31], v[174:177], v[186:189], v[16:31]
	v_mfma_f32_32x32x16_bf16 v[0:15], v[174:177], v[190:193], v[0:15]
	s_waitcnt vmcnt(8) lgkmcnt(0)
	s_barrier
	v_mfma_f32_32x32x16_bf16 v[112:127], v[212:215], v[220:223], v[112:127]
	ds_read_b128 v[170:173], v195 offset:32768
	s_mov_b32 m0, s15
	v_lshl_add_u64 v[136:137], v[130:131], 0, s[24:25]
	global_load_lds_dwordx4 v[136:137], off
	v_mfma_f32_32x32x16_bf16 v[96:111], v[212:215], v[224:227], v[96:111]
	ds_read_b128 v[174:177], v195 offset:34816
	s_add_u32 m0, s15, 0x2000
	v_lshl_add_u64 v[138:139], v[128:129], 0, s[24:25]
	global_load_lds_dwordx4 v[138:139], off
	v_mfma_f32_32x32x16_bf16 v[48:63], v[212:215], v[228:231], v[48:63]
	ds_read_b128 v[178:181], v196 offset:49152
	s_add_u32 m0, s15, 0x4000
	v_lshl_add_u64 v[136:137], v[134:135], 0, s[24:25]
	global_load_lds_dwordx4 v[136:137], off
	v_mfma_f32_32x32x16_bf16 v[32:47], v[212:215], v[232:235], v[32:47]
	ds_read_b128 v[182:185], v196 offset:51200
	s_add_u32 m0, s15, 0x6000
	v_lshl_add_u64 v[138:139], v[132:133], 0, s[24:25]
	global_load_lds_dwordx4 v[138:139], off
	ds_read_b128 v[212:215], v152 offset:32768
	s_add_u32 s24, s24, 64
	s_addc_u32 s25, s25, 0
	v_mfma_f32_32x32x16_bf16 v[80:95], v[216:219], v[220:223], v[80:95]
	ds_read_b128 v[186:189], v196 offset:53248
	ds_read_b128 v[220:223], v194 offset:49152
	v_mfma_f32_32x32x16_bf16 v[64:79], v[216:219], v[224:227], v[64:79]
	ds_read_b128 v[190:193], v196 offset:55296
	ds_read_b128 v[224:227], v194 offset:51200
	v_mfma_f32_32x32x16_bf16 v[16:31], v[216:219], v[228:231], v[16:31]
	ds_read_b128 v[228:231], v194 offset:53248
	v_mfma_f32_32x32x16_bf16 v[0:15], v[216:219], v[232:235], v[0:15]
	ds_read_b128 v[232:235], v194 offset:55296
	ds_read_b128 v[216:219], v152 offset:34816
	v_xor_b32_e32 v195, 0x10000, v195
	v_xor_b32_e32 v196, 0x10000, v196
	v_xor_b32_e32 v152, 0x10000, v152
	v_xor_b32_e32 v194, 0x10000, v194
	s_waitcnt lgkmcnt(4)
	v_mfma_f32_32x32x16_bf16 v[112:127], v[170:173], v[178:181], v[112:127]
	v_mfma_f32_32x32x16_bf16 v[96:111], v[170:173], v[182:185], v[96:111]
	v_mfma_f32_32x32x16_bf16 v[48:63], v[170:173], v[186:189], v[48:63]
	v_mfma_f32_32x32x16_bf16 v[32:47], v[170:173], v[190:193], v[32:47]
	v_mfma_f32_32x32x16_bf16 v[80:95], v[174:177], v[178:181], v[80:95]
	v_mfma_f32_32x32x16_bf16 v[64:79], v[174:177], v[182:185], v[64:79]
	v_mfma_f32_32x32x16_bf16 v[16:31], v[174:177], v[186:189], v[16:31]
	v_mfma_f32_32x32x16_bf16 v[0:15], v[174:177], v[190:193], v[0:15]
	s_waitcnt vmcnt(8) lgkmcnt(0)
	s_barrier
	v_mfma_f32_32x32x16_bf16 v[112:127], v[212:215], v[220:223], v[112:127]
	ds_read_b128 v[170:173], v195
	s_add_u32 m0, s15, 0x8000
	v_lshl_add_u64 v[136:137], v[130:131], 0, s[24:25]
	global_load_lds_dwordx4 v[136:137], off
	v_mfma_f32_32x32x16_bf16 v[96:111], v[212:215], v[224:227], v[96:111]
	ds_read_b128 v[174:177], v195 offset:2048
	s_add_u32 m0, s15, 0xa000
	v_lshl_add_u64 v[138:139], v[128:129], 0, s[24:25]
	global_load_lds_dwordx4 v[138:139], off
	v_mfma_f32_32x32x16_bf16 v[48:63], v[212:215], v[228:231], v[48:63]
	ds_read_b128 v[178:181], v196 offset:16384
	s_add_u32 m0, s15, 0xc000
	v_lshl_add_u64 v[136:137], v[134:135], 0, s[24:25]
	global_load_lds_dwordx4 v[136:137], off
	v_mfma_f32_32x32x16_bf16 v[32:47], v[212:215], v[232:235], v[32:47]
	ds_read_b128 v[182:185], v196 offset:18432
	s_add_u32 m0, s15, 0xe000
	v_lshl_add_u64 v[138:139], v[132:133], 0, s[24:25]
	global_load_lds_dwordx4 v[138:139], off
	ds_read_b128 v[212:215], v152
	s_add_u32 s24, s24, 64
	s_addc_u32 s25, s25, 0
	v_mfma_f32_32x32x16_bf16 v[80:95], v[216:219], v[220:223], v[80:95]
	ds_read_b128 v[186:189], v196 offset:20480
	ds_read_b128 v[220:223], v194 offset:16384
	v_mfma_f32_32x32x16_bf16 v[64:79], v[216:219], v[224:227], v[64:79]
	ds_read_b128 v[190:193], v196 offset:22528
	ds_read_b128 v[224:227], v194 offset:18432
	v_mfma_f32_32x32x16_bf16 v[16:31], v[216:219], v[228:231], v[16:31]
	ds_read_b128 v[228:231], v194 offset:20480
	v_mfma_f32_32x32x16_bf16 v[0:15], v[216:219], v[232:235], v[0:15]
	ds_read_b128 v[232:235], v194 offset:22528
	ds_read_b128 v[216:219], v152 offset:2048
	s_xor_b32 s15, s15, 0x10000
	s_add_u32 s2, s2, 0x80
	s_cmpk_lg_i32 s2, 0x1000
	s_cbranch_scc1 .Lgm_p5e_loop
; DI float red8(float s) { s += __shfl_xor(s, 1); s += __shfl_xor(s, 2); s += __shfl_xor(s, 4); return s; }
; DI void p5_tile(const Params& P, int l, int half, int t, char* smem) {
;     ...
;   _Pragma("unroll") for (int seg = 0; seg < 2; ++seg) {
;     const int gc = n0 + wn * 128 + seg * 64 + ch * 8;
;     _Pragma("unroll") for (int mi = 0; mi < 2; ++mi) {
;       stage_block(acc[mi][2 * seg], acc[mi][2 * seg + 1], sE, r, h);
;       _Pragma("unroll") for (int ps = 0; ps < 4; ++ps) {
;         const int rr = ps * 8 + (lane >> 3);
;         const int m = m0 + wm * 64 + mi * 32 + rr;
;         const size_t off = (size_t)m * DM + gc;
;         float v[8]; read8(sE + rr * EST + ch * 8, v);
;         float x[8]; read8(xin + off, x);
;         _Pragma("unroll") for (int j = 0; j < 8; ++j) v[j] += x[j];
;         *(float4*)(xo + off) = make_float4(v[0], v[1], v[2], v[3]);
;         *(float4*)(xo + off + 4) = make_float4(v[4], v[5], v[6], v[7]);
;         if (l < DEPTH - 1) {
;           *(u32x4*)(xbo + off) = pack8u(v);
;           float sq = red8(sum8sq(v));
;           if (ch == 0) sqn[(size_t)m * 32 + ((n0 + wn * 128 + seg * 64) >> 6)] = sq;
;         }
;       }
	s_waitcnt lgkmcnt(0)
	s_mov_b64 s[24:25], 0xc0
	s_movk_i32 s1, 0x2200
	v_mul_lo_u32 v128, v159, s1
	v_mul_u32_u24_e32 v129, 0x110, v158
	v_add_u32_e32 v130, 0, v128
	v_lshlrev_b32_e32 v129, 2, v129
	v_lshlrev_b32_e32 v132, 2, v156
	v_add3_u32 v134, v130, v129, v132
	v_add3_u32 v135, v130, v132, v129
	v_and_b32_e32 v131, 7, v157
	v_lshrrev_b32_e32 v129, 3, v154
	v_add_u32_e32 v143, s0, v155
	v_add_u32_e32 v136, 0x800, v134
	v_add_u32_e32 v137, 0x800, v135
	v_add_u32_e32 v140, 0x1000, v135
	s_waitcnt vmcnt(0)
	s_waitcnt vmcnt(0)
	s_barrier
	v_or_b32_e32 v128, s14, v160
	v_lshlrev_b32_e32 v152, 3, v131
	ds_write2_b32 v134, v112, v113 offset1:68
	ds_write2_b32 v135, v96, v97 offset0:32 offset1:100
	ds_write2_b32 v134, v114, v115 offset0:136 offset1:204
	ds_write2_b32 v135, v98, v99 offset0:168 offset1:236
	ds_write2_b32 v136, v116, v117 offset0:32 offset1:100
	ds_write2_b32 v137, v100, v101 offset0:64 offset1:132
	ds_write2_b32 v136, v118, v119 offset0:168 offset1:236
	ds_write2_b32 v140, v104, v105 offset0:96 offset1:164
	v_or_b32_e32 v104, v143, v129
	v_or_b32_e32 v132, v128, v152
	v_add_u32_e32 v141, 0x1200, v134
	v_ashrrev_i32_e32 v105, 31, v104
	v_ashrrev_i32_e32 v133, 31, v132
	ds_write2_b32 v141, v122, v123 offset0:72 offset1:140
	v_add_u32_e32 v123, 0x1200, v135
	v_add_u32_e32 v142, 0x1800, v134
	v_lshlrev_b64 v[112:113], 11, v[104:105]
	ds_write2_b32 v123, v106, v107 offset0:104 offset1:172
	ds_write2_b32 v142, v124, v125 offset0:96 offset1:164
	v_add_u32_e32 v125, 0x1a00, v134
	v_lshl_add_u64 v[106:107], v[112:113], 0, v[132:133]
	v_lshl_add_u32 v154, v131, 5, v130
	v_add_u32_e32 v138, 0xa00, v135
	v_add_u32_e32 v139, 0x1000, v134
	v_add_u32_e32 v124, 0x1800, v135
	ds_write2_b32 v125, v126, v127 offset0:104 offset1:172
	v_add_u32_e32 v126, 0x1c00, v135
	s_movk_i32 s2, 0x110
	v_lshlrev_b64 v[118:119], 2, v[106:107]
	ds_write2_b32 v138, v102, v103 offset0:72 offset1:140
	ds_write2_b32 v139, v120, v121 offset0:64 offset1:132
	ds_write2_b32 v124, v108, v109 offset0:128 offset1:196
	ds_write2_b32 v126, v110, v111 offset0:8 offset1:76
	v_mad_u32_u24 v102, v129, s2, v154
	v_lshl_add_u64 v[100:101], s[6:7], 0, v[118:119]
	ds_read_b128 v[96:99], v102
	ds_read_b128 v[108:111], v102 offset:16
	global_load_dwordx4 v[114:117], v[100:101], off offset:16
	s_nop 0
	global_load_dwordx4 v[100:103], v[100:101], off
	v_ashrrev_i32_e32 v130, 6, v128
	v_cmp_eq_u32_e64 s[0:1], 0, v131
	v_ashrrev_i32_e32 v131, 31, v130
	v_lshl_add_u64 v[130:131], v[130:131], 2, s[10:11]
	s_andn2_b64 vcc, exec, s[12:13]
	s_waitcnt vmcnt(0) lgkmcnt(1)
	v_pk_add_f32 v[100:101], v[96:97], v[100:101]
	v_pk_add_f32 v[102:103], v[98:99], v[102:103]
	s_waitcnt lgkmcnt(0)
	v_pk_add_f32 v[96:97], v[108:109], v[114:115]
	v_lshl_add_u64 v[108:109], s[4:5], 0, v[118:119]
	v_pk_add_f32 v[98:99], v[110:111], v[116:117]
	global_store_dwordx4 v[108:109], v[100:103], off
	global_store_dwordx4 v[108:109], v[96:99], off offset:16
	v_cndmask_b32_e64 v108, 0, 1, s[12:13]
	v_cmp_ne_u32_e64 s[2:3], 1, v108
	s_cbranch_vccnz .LBB0_757
	v_cvt_pk_bf16_f32 v108, v100, v101
	v_pk_mul_f32 v[100:101], v[100:101], v[100:101]
	v_cvt_pk_bf16_f32 v109, v102, v103
	v_pk_mul_f32 v[102:103], v[102:103], v[102:103]
	v_add_f32_e32 v100, v100, v101
	v_add_f32_e32 v100, v102, v100
	v_cvt_pk_bf16_f32 v110, v96, v97
	v_pk_mul_f32 v[96:97], v[96:97], v[96:97]
	v_add_f32_e32 v100, v103, v100
	v_add_f32_e32 v96, v96, v100
	v_add_f32_e32 v96, v97, v96
	v_xor_b32_e32 v97, 1, v145
	v_cvt_pk_bf16_f32 v111, v98, v99
	v_pk_mul_f32 v[98:99], v[98:99], v[98:99]
	v_cmp_lt_i32_e32 vcc, v97, v198
	v_add_f32_e32 v96, v98, v96
	v_add_f32_e32 v96, v99, v96
	v_cndmask_b32_e32 v97, v145, v97, vcc
	v_lshlrev_b32_e32 v97, 2, v97
	ds_bpermute_b32 v97, v97, v96
	v_lshl_add_u64 v[106:107], v[106:107], 1, s[8:9]
	global_store_dwordx4 v[106:107], v[108:111], off
	s_waitcnt lgkmcnt(0)
	v_add_f32_e32 v96, v96, v97
	v_xor_b32_e32 v97, 2, v145
	v_cmp_lt_i32_e32 vcc, v97, v198
	s_nop 1
	v_cndmask_b32_e32 v97, v145, v97, vcc
	v_lshlrev_b32_e32 v97, 2, v97
	ds_bpermute_b32 v97, v97, v96
	s_waitcnt lgkmcnt(0)
	v_add_f32_e32 v96, v96, v97
	v_xor_b32_e32 v97, 4, v145
	v_cmp_lt_i32_e32 vcc, v97, v198
	s_nop 1
	v_cndmask_b32_e32 v97, v145, v97, vcc
	v_lshlrev_b32_e32 v97, 2, v97
	ds_bpermute_b32 v97, v97, v96
	s_and_saveexec_b64 s[14:15], s[0:1]
	s_cbranch_execz .LBB0_756
	s_waitcnt lgkmcnt(0)
	v_add_f32_e32 v98, v96, v97
	v_lshlrev_b64 v[96:97], 7, v[104:105]
	v_lshl_add_u64 v[96:97], v[130:131], 0, v[96:97]
	global_store_dword v[96:97], v98, off

; DI int tid_opaque() { int t = threadIdx.x; asm volatile("" : "+v"(t)); return t; }
; DI void dma_stage(const bf16_t* __restrict__ A, int lda, const bf16_t* __restrict__ B, int ldb, int k0, char* stage, int w, int lane) {
;   const int lr = lane >> 2, pos = lane & 3;
;   _Pragma("unroll") for (int i = 0; i < 4; ++i) {
;     const int idx = w + 8 * i;
;     const int row = (idx << 4) + lr;
;     const int c = pos ^ ((row >> 2) & 3);
;     const bf16_t* g = (i < 2) ? (A + (size_t)row * lda + k0 + c * 8) : (B + (size_t)(row - 256) * ldb + k0 + c * 8);
;     __builtin_amdgcn_global_load_lds((const unsigned*)g, (unsigned*)(stage + idx * 1024 + lane * 16), 16, 0, 0);
;   }
; }
; DI void gemm_mainloop(const bf16_t* __restrict__ A, int lda, const bf16_t* __restrict__ B, int ldb, int K,
;                       f32x16 (&acc)[2][4], char* smem, const int tid) {
;   const int lane = tid & 63, w = tid >> 6;
;   const int wm = w >> 1, wn = w & 1, r = lane & 31, h = lane >> 5;
;   const int swz = (r >> 2) & 3;
;   const int o0 = ((0 + h) ^ swz) << 4, o1 = ((2 + h) ^ swz) << 4;
;   const int aoff = (wm * 64 + r) * 64, boff = (256 + wn * 128 + r) * 64;
;   const int nk = K >> 5;
;   dma_stage(A, lda, B, ldb, 0, smem, w, lane);
;   dma_stage(A, lda, B, ldb, 32, smem + STG, w, lane);
;   dma_stage(A, lda, B, ldb, 64, smem + 2 * STG, w, lane);
; DI void p1_tile(const Params& P, int l, int half, int t, char* smem) {
;   int tm, tn; tile_decode(t, 44, tm, tn);
;   const int m0 = tm * 256, n0 = tn * 256;
;   const int tid = tid_opaque(), lane = tid & 63, w = tid >> 6, wm = w >> 1, wn = w & 1, r = lane & 31, h = lane >> 5;
;   f32x16 acc[2][4]; zero_acc(acc);
;   const float rsum = rstd_prefetch<32>(P.sq_x + ((size_t)half * TH + m0) * 32, tid);
;   gemm_mainloop(P.xb + ((size_t)half * TH + m0) * DM, DM, P.wt_in + ((size_t)l * NINP + n0) * DM, DM, DM, acc, smem, tid);
.LBB0_923:
	s_mul_hi_i32 s0, s13, 0x2e8ba2e9
	s_lshr_b32 s1, s0, 31
	s_ashr_i32 s4, s0, 6
	s_add_i32 s4, s4, s1
	s_lshl_b32 s0, s13, 8
	s_lshl_b32 s5, s4, 11
	s_and_b32 s0, s0, 0x700
	s_or_b32 s14, s5, s0
	s_ashr_i32 s15, s14, 31
	v_mov_b32_e32 v128, v144
	s_add_u32 s0, s14, s75
	s_movk_i32 s2, 0x100
	s_addc_u32 s1, s15, 0
	v_cmp_gt_i32_e32 vcc, s2, v128
	v_mov_b32_e32 v135, 0x358637bd
	s_mov_b64 s[98:99], s[0:1]
	v_ashrrev_i32_e32 v207, 1, v128
	s_mul_i32 s2, s4, 0xfffffea0
	v_and_b32_e32 v208, 31, v128
	v_and_b32_e32 v134, 0xffffffc0, v207
	s_add_i32 s2, s2, s13
	v_ashrrev_i32_e32 v160, 6, v128
	v_or_b32_e32 v0, v134, v208
	s_lshl_b32 s77, s2, 5
	v_readlane_b32 s16, v249, 18
	v_lshlrev_b32_e32 v162, 6, v0
	v_lshlrev_b32_e32 v0, 7, v160
	s_and_b32 s8, s12, 0x700
	s_and_b32 s3, s77, 0xffffff00
	s_lshl_b64 s[0:1], s[0:1], 12
	v_readlane_b32 s30, v249, 32
	v_and_b32_e32 v161, 0x80, v0
	v_readlane_b32 s17, v249, 19
	v_readlane_b32 s18, v249, 20
	v_readlane_b32 s19, v249, 21
	v_readlane_b32 s20, v249, 22
	v_readlane_b32 s21, v249, 23
	v_readlane_b32 s22, v249, 24
	v_readlane_b32 s23, v249, 25
	v_readlane_b32 s24, v249, 26
	v_readlane_b32 s25, v249, 27
	v_readlane_b32 s26, v249, 28
	v_readlane_b32 s27, v249, 29
	v_readlane_b32 s28, v249, 30
	v_readlane_b32 s29, v249, 31
	v_readlane_b32 s31, v249, 33
	s_add_u32 s0, s30, s0
	v_or_b32_e32 v0, v161, v208
	v_and_b32_e32 v129, 63, v128
	s_addc_u32 s1, s31, s1
	s_ashr_i32 s7, s3, 31
	v_readlane_b32 s16, v249, 38
	v_lshlrev_b32_e32 v163, 6, v0
	v_bfe_u32 v12, v128, 2, 4
	v_bfe_u32 v0, v128, 4, 2
	v_add_u32_e32 v13, 8, v160
	s_add_u32 s6, s3, s76
	v_readlane_b32 s20, v249, 42
	v_readlane_b32 s21, v249, 43
	v_readlane_b32 s22, v249, 44
	v_readlane_b32 s23, v249, 45
	v_readlane_b32 s28, v249, 50
	v_readlane_b32 s29, v249, 51
	v_bitop3_b32 v0, v0, v128, 3 bitop3:0x78
	v_lshlrev_b32_e32 v16, 4, v129
	v_lshl_or_b32 v4, v160, 4, v12
	v_lshl_or_b32 v10, v13, 4, v12
	s_addc_u32 s7, s7, 0
	v_readlane_b32 s30, v249, 52
	v_readlane_b32 s31, v249, 53
	s_mov_b64 s[20:21], s[28:29]
	v_add_u32_e32 v164, 0, v16
	v_lshlrev_b32_e32 v152, 4, v0
	v_ashrrev_i32_e32 v5, 31, v4
	v_lshlrev_b32_e32 v165, 10, v160
	v_ashrrev_i32_e32 v11, 31, v10
	s_lshl_b64 s[6:7], s[6:7], 12
	s_mov_b64 s[22:23], s[30:31]
	v_lshl_add_u64 v[2:3], s[0:1], 0, v[152:153]
	v_lshlrev_b64 v[6:7], 12, v[4:5]
	v_add_u32_e32 v5, v164, v165
	v_lshlrev_b64 v[10:11], 12, v[10:11]
	v_lshlrev_b32_e32 v166, 10, v13
	v_add_u32_e32 v13, 16, v160
	v_or_b32_e32 v12, 0xffffff00, v12
	s_add_u32 s6, s22, s6
	v_lshl_add_u64 v[8:9], v[2:3], 0, v[6:7]
	v_readfirstlane_b32 s0, v5
	v_lshl_add_u64 v[2:3], v[2:3], 0, v[10:11]
	v_add_u32_e32 v17, v164, v166
	v_lshl_add_u32 v10, v13, 4, v12
	v_lshlrev_b32_e32 v167, 10, v13
	v_add_u32_e32 v19, 24, v160
	s_addc_u32 s7, s23, s7
	s_mov_b32 m0, s0
	v_readfirstlane_b32 s0, v17
	v_ashrrev_i32_e32 v11, 31, v10
	v_add_u32_e32 v18, v164, v167
	v_lshl_add_u32 v12, v19, 4, v12
	v_lshlrev_b32_e32 v168, 10, v19
	v_lshl_add_u64 v[0:1], s[6:7], 0, v[152:153]
	global_load_lds_dwordx4 v[8:9], off
	s_mov_b32 m0, s0
	v_lshlrev_b64 v[10:11], 12, v[10:11]
	v_readfirstlane_b32 s0, v18
	v_ashrrev_i32_e32 v13, 31, v12
	v_add_u32_e32 v19, v164, v168
	global_load_lds_dwordx4 v[2:3], off
	v_lshl_add_u64 v[10:11], v[0:1], 0, v[10:11]
	s_mov_b32 m0, s0
	v_lshlrev_b64 v[12:13], 12, v[12:13]
	v_readfirstlane_b32 s0, v19
	v_add_u32_e32 v5, 0x8000, v5
	global_load_lds_dwordx4 v[10:11], off
	v_lshl_add_u64 v[0:1], v[0:1], 0, v[12:13]
	s_mov_b32 m0, s0
	v_readfirstlane_b32 s0, v5
	v_add_u32_e32 v5, 0x8000, v17
	global_load_lds_dwordx4 v[0:1], off
	v_lshl_add_u64 v[12:13], v[8:9], 0, 64
	s_mov_b32 m0, s0
	v_readfirstlane_b32 s0, v5
	v_add_u32_e32 v5, 0x8000, v18
	global_load_lds_dwordx4 v[12:13], off
	v_lshl_add_u64 v[12:13], v[2:3], 0, 64
	s_mov_b32 m0, s0
	v_readfirstlane_b32 s0, v5
	v_add_u32_e32 v5, 0x8000, v19
	global_load_lds_dwordx4 v[12:13], off
	v_lshl_add_u64 v[12:13], v[10:11], 0, 64
	s_mov_b32 m0, s0
	v_readfirstlane_b32 s0, v5
	global_load_lds_dwordx4 v[12:13], off
	s_mov_b32 m0, s0
	s_add_i32 s0, 0, 0x10000
	v_lshl_add_u64 v[12:13], v[0:1], 0, 64
	v_add_u32_e32 v5, s0, v16
	global_load_lds_dwordx4 v[12:13], off
	v_add_u32_e32 v12, v5, v165
	s_mov_b64 s[6:7], 0x80
	v_readfirstlane_b32 s0, v12
	v_lshl_add_u64 v[8:9], v[8:9], 0, s[6:7]
	s_mov_b32 m0, s0
	v_lshl_add_u64 v[2:3], v[2:3], 0, s[6:7]
	global_load_lds_dwordx4 v[8:9], off
	v_add_u32_e32 v8, v5, v166
	v_lshl_add_u64 v[0:1], v[0:1], 0, s[6:7]
	v_readfirstlane_b32 s0, v8
	v_add_u32_e32 v8, v5, v167
	s_mov_b32 m0, s0
	v_readfirstlane_b32 s0, v8
	global_load_lds_dwordx4 v[2:3], off
	v_lshl_add_u64 v[2:3], v[10:11], 0, s[6:7]
	s_mov_b32 m0, s0
	v_bfe_u32 v209, v128, 5, 1
	global_load_lds_dwordx4 v[2:3], off
	v_add_u32_e32 v2, v5, v168
	v_lshrrev_b32_e32 v14, 2, v128
	v_readfirstlane_b32 s0, v2
	s_mov_b32 m0, s0
	v_bfe_u32 v15, v128, 2, 2
	global_load_lds_dwordx4 v[0:1], off
	v_bitop3_b32 v0, v209, v14, 3 bitop3:0x78
	v_lshlrev_b32_e32 v169, 4, v0
	v_bitop3_b32 v0, v209, v15, 2 bitop3:0x36
	v_readlane_b32 s17, v249, 39
	v_lshlrev_b32_e32 v170, 4, v0
	v_add_u32_e32 v0, 0x80, v4
	s_add_i32 s16, s5, s8
	v_ashrrev_i32_e32 v1, 31, v0
	s_ashr_i32 s17, s16, 31
	v_lshlrev_b64 v[0:1], 12, v[0:1]
	s_lshl_b64 s[0:1], s[16:17], 12
	v_lshl_add_u64 v[2:3], v[0:1], 0, s[0:1]
	v_or_b32_e32 v2, v2, v152
	s_mulk_i32 s4, 0x2c00
	v_lshl_add_u64 v[130:131], v[132:133], 0, v[2:3]
	v_lshl_add_u64 v[2:3], s[0:1], 0, v[6:7]
	s_sub_i32 s0, s97, s4
	s_and_b32 s0, s0, 0xffffff00
	s_ashr_i32 s1, s0, 31
	s_lshl_b64 s[0:1], s[0:1], 12
	v_lshl_add_u64 v[0:1], s[0:1], 0, v[0:1]
	v_or_b32_e32 v0, v0, v152
	v_lshl_add_u64 v[138:139], s[80:81], 0, v[0:1]
	v_lshl_add_u64 v[0:1], s[0:1], 0, v[6:7]
	v_or_b32_e32 v0, v0, v152
	v_or_b32_e32 v2, v2, v152
	v_lshl_add_u64 v[140:141], s[80:81], 0, v[0:1]
	v_mov_b32_e32 v0, 0
	v_lshl_add_u64 v[136:137], v[132:133], 0, v[2:3]
	s_and_saveexec_b64 s[100:101], vcc
	s_cbranch_execz .Lp1m_rstd_done
; DI void gemm_mainloop(const bf16_t* __restrict__ A, int lda, const bf16_t* __restrict__ B, int ldb, int K,
;                       f32x16 (&acc)[2][4], char* smem, const int tid) {
;     ...
;   dma_stage(A, lda, B, ldb, 0, smem, w, lane);
;   dma_stage(A, lda, B, ldb, 32, smem + STG, w, lane);
;   dma_stage(A, lda, B, ldb, 64, smem + 2 * STG, w, lane);
;   for (int kt = 0; kt < nk; ++kt) {
;     asm volatile("s_waitcnt vmcnt(8) lgkmcnt(0)" ::: "memory");
;     __builtin_amdgcn_s_barrier();
;     dma_stage(A, lda, B, ldb, (kt + 3) * 32, smem + ((kt + 3) & 3) * STG, w, lane);
; template <int NP>
; DI float rstd_prefetch(const float* part, int tid) {
;   float s = 0.f;
;   if (tid < 256) {
;     _Pragma("unroll") for (int i = 0; i < NP / 4; ++i) {
;       float4 q = *(const float4*)(part + (size_t)tid * NP + i * 4);
;       s += (q.x + q.y) + (q.z + q.w);
;     }
;   }
;   return s;
; }
	s_lshl_b64 s[6:7], s[98:99], 7
	s_add_u32 s6, s62, s6
	v_mov_b32_e32 v26, v128
	v_ashrrev_i32_e32 v27, 31, v128
	s_addc_u32 s7, s63, s7
	v_lshlrev_b64 v[0:1], 7, v[26:27]
	v_lshl_add_u64 v[16:17], s[6:7], 0, v[0:1]
	global_load_dwordx4 v[0:3], v[16:17], off offset:48
	global_load_dwordx4 v[4:7], v[16:17], off offset:32
	global_load_dwordx4 v[8:11], v[16:17], off offset:16
	global_load_dwordx4 v[12:15], v[16:17], off
	s_waitcnt vmcnt(2)
	v_mov_b32_e32 v18, v5
	s_waitcnt vmcnt(1)
	v_mov_b32_e32 v21, v8
	s_waitcnt vmcnt(0)
	v_mov_b32_e32 v20, v12
	v_mov_b32_e32 v8, v13
	v_mov_b32_e32 v12, v14
	v_mov_b32_e32 v13, v10
	v_mov_b32_e32 v10, v15
	v_pk_add_f32 v[8:9], v[20:21], v[8:9]
	v_pk_add_f32 v[10:11], v[12:13], v[10:11]
	v_mov_b32_e32 v19, v6
	v_pk_add_f32 v[8:9], v[8:9], v[10:11]
	s_nop 0
	v_add_f32_e32 v5, 0, v8
	v_add_f32_e32 v20, v5, v9
	v_mov_b32_e32 v5, v7
	v_pk_add_f32 v[4:5], v[18:19], v[4:5]
	s_nop 0
	v_pk_add_f32 v[18:19], v[4:5], v[4:5] op_sel:[0,1] op_sel_hi:[1,0]
	v_mov_b32_e32 v4, v1
	v_pk_add_f32 v[22:23], v[0:1], v[4:5]
	v_mov_b32_e32 v0, v3
	v_pk_add_f32 v[24:25], v[2:3], v[0:1]
	global_load_dwordx4 v[0:3], v[16:17], off offset:96
	global_load_dwordx4 v[4:7], v[16:17], off offset:80
	global_load_dwordx4 v[8:11], v[16:17], off offset:112
	global_load_dwordx4 v[12:15], v[16:17], off offset:64
	s_waitcnt vmcnt(2)
	v_mov_b32_e32 v16, v5
	v_mov_b32_e32 v17, v6
	s_waitcnt vmcnt(0)
	v_mov_b32_e32 v21, v12
	v_mov_b32_e32 v19, v13
	v_mov_b32_e32 v23, v14
	v_mov_b32_e32 v25, v15
	v_pk_add_f32 v[12:13], v[20:21], v[18:19]
	v_pk_add_f32 v[14:15], v[22:23], v[24:25]
	v_mov_b32_e32 v5, v7
	v_mov_b32_e32 v6, v1
	v_pk_add_f32 v[12:13], v[12:13], v[14:15]
	v_pk_add_f32 v[4:5], v[16:17], v[4:5]
	v_pk_add_f32 v[0:1], v[0:1], v[6:7]
	v_mov_b32_e32 v6, v3
	v_pk_add_f32 v[12:13], v[12:13], v[12:13] op_sel:[0,1] op_sel_hi:[1,0]
	v_pk_add_f32 v[4:5], v[4:5], v[4:5] op_sel:[0,1] op_sel_hi:[1,0]
	v_pk_add_f32 v[2:3], v[2:3], v[6:7]
	v_mov_b32_e32 v13, v8
	v_mov_b32_e32 v5, v9
	v_mov_b32_e32 v1, v10
	v_mov_b32_e32 v3, v11
	v_pk_add_f32 v[4:5], v[12:13], v[4:5]
	v_pk_add_f32 v[0:1], v[0:1], v[2:3]
	s_nop 0
	v_pk_add_f32 v[0:1], v[4:5], v[0:1]
	s_nop 0
	v_add_f32_e32 v0, v0, v1
	v_fmamk_f32 v135, v0, 0x3a000000, v201
.Lp1m_rstd_done:
	s_or_b64 exec, exec, s[100:101]
	v_mov_b32_e32 v0, 0
	s_mov_b64 s[0:1], 0
	s_mov_b32 s4, 0
	v_mov_b32_e32 v1, v0
	v_mov_b32_e32 v2, v0
	v_mov_b32_e32 v3, v0
	v_mov_b32_e32 v4, v0
	v_mov_b32_e32 v5, v0
	v_mov_b32_e32 v6, v0
	v_mov_b32_e32 v7, v0
	v_mov_b32_e32 v8, v0
	v_mov_b32_e32 v9, v0
	v_mov_b32_e32 v10, v0
	v_mov_b32_e32 v11, v0
	v_mov_b32_e32 v12, v0
	v_mov_b32_e32 v13, v0
	v_mov_b32_e32 v14, v0
	v_mov_b32_e32 v15, v0
	v_mov_b32_e32 v16, v0
	v_mov_b32_e32 v17, v0
	v_mov_b32_e32 v18, v0
	v_mov_b32_e32 v19, v0
	v_mov_b32_e32 v20, v0
	v_mov_b32_e32 v21, v0
	v_mov_b32_e32 v22, v0
	v_mov_b32_e32 v23, v0
	v_mov_b32_e32 v24, v0
	v_mov_b32_e32 v25, v0
	v_mov_b32_e32 v26, v0
	v_mov_b32_e32 v27, v0
	v_mov_b32_e32 v28, v0
	v_mov_b32_e32 v29, v0
	v_mov_b32_e32 v30, v0
	v_mov_b32_e32 v31, v0
	v_mov_b32_e32 v64, v0
	v_mov_b32_e32 v65, v0
	v_mov_b32_e32 v66, v0
	v_mov_b32_e32 v67, v0
	v_mov_b32_e32 v68, v0
	v_mov_b32_e32 v69, v0
	v_mov_b32_e32 v70, v0
	v_mov_b32_e32 v71, v0
	v_mov_b32_e32 v72, v0
	v_mov_b32_e32 v73, v0
	v_mov_b32_e32 v74, v0
	v_mov_b32_e32 v75, v0
	v_mov_b32_e32 v76, v0
	v_mov_b32_e32 v77, v0
	v_mov_b32_e32 v78, v0
	v_mov_b32_e32 v79, v0
	v_mov_b32_e32 v80, v0
	v_mov_b32_e32 v81, v0
	v_mov_b32_e32 v82, v0
	v_mov_b32_e32 v83, v0
	v_mov_b32_e32 v84, v0
	v_mov_b32_e32 v85, v0
	v_mov_b32_e32 v86, v0
	v_mov_b32_e32 v87, v0
	v_mov_b32_e32 v88, v0
	v_mov_b32_e32 v89, v0
	v_mov_b32_e32 v90, v0
	v_mov_b32_e32 v91, v0
	v_mov_b32_e32 v92, v0
	v_mov_b32_e32 v93, v0
	v_mov_b32_e32 v94, v0
	v_mov_b32_e32 v95, v0
	v_mov_b32_e32 v32, v0
	v_mov_b32_e32 v33, v0
	v_mov_b32_e32 v34, v0
	v_mov_b32_e32 v35, v0
	v_mov_b32_e32 v36, v0
	v_mov_b32_e32 v37, v0
	v_mov_b32_e32 v38, v0
	v_mov_b32_e32 v39, v0
	v_mov_b32_e32 v40, v0
	v_mov_b32_e32 v41, v0
	v_mov_b32_e32 v42, v0
	v_mov_b32_e32 v43, v0
	v_mov_b32_e32 v44, v0
	v_mov_b32_e32 v45, v0
	v_mov_b32_e32 v46, v0
	v_mov_b32_e32 v47, v0
	v_mov_b32_e32 v48, v0
	v_mov_b32_e32 v49, v0
	v_mov_b32_e32 v50, v0
	v_mov_b32_e32 v51, v0
	v_mov_b32_e32 v52, v0
	v_mov_b32_e32 v53, v0
	v_mov_b32_e32 v54, v0
	v_mov_b32_e32 v55, v0
	v_mov_b32_e32 v56, v0
	v_mov_b32_e32 v57, v0
	v_mov_b32_e32 v58, v0
	v_mov_b32_e32 v59, v0
	v_mov_b32_e32 v60, v0
	v_mov_b32_e32 v61, v0
	v_mov_b32_e32 v62, v0
	v_mov_b32_e32 v63, v0
	v_mov_b32_e32 v96, v0
	v_mov_b32_e32 v97, v0
	v_mov_b32_e32 v98, v0
	v_mov_b32_e32 v99, v0
	v_mov_b32_e32 v100, v0
	v_mov_b32_e32 v101, v0
	v_mov_b32_e32 v102, v0
	v_mov_b32_e32 v103, v0
	v_mov_b32_e32 v104, v0
	v_mov_b32_e32 v105, v0
	v_mov_b32_e32 v106, v0
	v_mov_b32_e32 v107, v0
	v_mov_b32_e32 v108, v0
	v_mov_b32_e32 v109, v0
	v_mov_b32_e32 v110, v0
	v_mov_b32_e32 v111, v0
	v_mov_b32_e32 v112, v0
	v_mov_b32_e32 v113, v0
	v_mov_b32_e32 v114, v0
	v_mov_b32_e32 v115, v0
	v_mov_b32_e32 v116, v0
	v_mov_b32_e32 v117, v0
	v_mov_b32_e32 v118, v0
	v_mov_b32_e32 v119, v0
	v_mov_b32_e32 v120, v0
	v_mov_b32_e32 v121, v0
	v_mov_b32_e32 v122, v0
	v_mov_b32_e32 v123, v0
	v_mov_b32_e32 v124, v0
	v_mov_b32_e32 v125, v0
	v_mov_b32_e32 v126, v0
	v_mov_b32_e32 v127, v0
	s_mov_b64 s[8:9], 0xc0
	s_mov_b64 s[10:11], 0x100
	v_readlane_b32 s18, v249, 40
	v_readlane_b32 s19, v249, 41
	v_readlane_b32 s24, v249, 46
	v_readlane_b32 s25, v249, 47
	v_readlane_b32 s26, v249, 48
	v_readlane_b32 s27, v249, 49
	v_add_u32_e32 v205, v164, v165
	v_add_u32_e32 v196, v162, v169
	v_add_u32_e32 v197, v163, v169
	v_readfirstlane_b32 s5, v205
	v_add_u32_e32 v152, v162, v170
	v_add_u32_e32 v171, v163, v170
	s_waitcnt vmcnt(8) lgkmcnt(0)
	s_barrier
	ds_read_b128 v[172:175], v196
	ds_read_b128 v[176:179], v196 offset:2048
	ds_read_b128 v[180:183], v197 offset:16384
	ds_read_b128 v[184:187], v197 offset:18432
	ds_read_b128 v[188:191], v197 offset:20480
	ds_read_b128 v[192:195], v197 offset:22528
	ds_read_b128 v[212:215], v152
	ds_read_b128 v[216:219], v152 offset:2048
	ds_read_b128 v[220:223], v171 offset:16384
	ds_read_b128 v[224:227], v171 offset:18432
	ds_read_b128 v[228:231], v171 offset:20480
	ds_read_b128 v[232:235], v171 offset:22528
	s_add_u32 m0, s5, 0x18000
	v_lshl_add_u64 v[142:143], v[136:137], 0, s[8:9]
	v_lshl_add_u64 v[154:155], v[130:131], 0, s[8:9]
	global_load_lds_dwordx4 v[142:143], off
	s_add_u32 m0, s5, 0x1a000
	v_lshl_add_u64 v[142:143], v[140:141], 0, s[8:9]
	global_load_lds_dwordx4 v[154:155], off
	s_add_u32 m0, s5, 0x1c000
	v_lshl_add_u64 v[154:155], v[138:139], 0, s[8:9]
	global_load_lds_dwordx4 v[142:143], off
	s_add_u32 m0, s5, 0x1e000
	s_add_u32 s8, s8, 64
	global_load_lds_dwordx4 v[154:155], off
	s_addc_u32 s9, s9, 0
; #define MFMA32(a, b, c) __builtin_amdgcn_mfma_f32_32x32x16_bf16((a), (b), (c), 0, 0, 0)
; DI void gemm_mainloop(const bf16_t* __restrict__ A, int lda, const bf16_t* __restrict__ B, int ldb, int K,
;                       f32x16 (&acc)[2][4], char* smem, const int tid) {
;     ...
;   for (int kt = 0; kt < nk; ++kt) {
;     asm volatile("s_waitcnt vmcnt(8) lgkmcnt(0)" ::: "memory");
;     __builtin_amdgcn_s_barrier();
;     dma_stage(A, lda, B, ldb, (kt + 3) * 32, smem + ((kt + 3) & 3) * STG, w, lane);
;     const char* st = smem + (kt & 3) * STG;
;     _Pragma("unroll") for (int ks = 0; ks < 2; ++ks) {
;       const int oo = ks ? o1 : o0;
;       bf16x8 a0 = *(const bf16x8*)(st + aoff + oo);
;       bf16x8 a1 = *(const bf16x8*)(st + aoff + 32 * 64 + oo);
;       bf16x8 b0 = *(const bf16x8*)(st + boff + oo);
;       bf16x8 b1 = *(const bf16x8*)(st + boff + 32 * 64 + oo);
;       bf16x8 b2 = *(const bf16x8*)(st + boff + 64 * 64 + oo);
;       bf16x8 b3 = *(const bf16x8*)(st + boff + 96 * 64 + oo);
;       acc[0][0] = MFMA32(a0, b0, acc[0][0]); acc[0][1] = MFMA32(a0, b1, acc[0][1]);
;       acc[0][2] = MFMA32(a0, b2, acc[0][2]); acc[0][3] = MFMA32(a0, b3, acc[0][3]);
;       acc[1][0] = MFMA32(a1, b0, acc[1][0]); acc[1][1] = MFMA32(a1, b1, acc[1][1]);
;       acc[1][2] = MFMA32(a1, b2, acc[1][2]); acc[1][3] = MFMA32(a1, b3, acc[1][3]);
;     }
;   }
;   asm volatile("s_waitcnt vmcnt(0)" ::: "memory");
;   __syncthreads();
; DI void rstd_publish(float s, float invK, float* srstd, int tid) {
;   if (tid < 256) srstd[tid] = rsqrtf(s * invK + EPS);
;   __syncthreads();
.Lgm_p1m_loop:
	s_waitcnt lgkmcnt(4)
	v_mfma_f32_32x32x16_bf16 v[112:127], v[172:175], v[180:183], v[112:127]
	v_mfma_f32_32x32x16_bf16 v[96:111], v[172:175], v[184:187], v[96:111]
	v_mfma_f32_32x32x16_bf16 v[48:63], v[172:175], v[188:191], v[48:63]
	v_mfma_f32_32x32x16_bf16 v[32:47], v[172:175], v[192:195], v[32:47]
	v_mfma_f32_32x32x16_bf16 v[80:95], v[176:179], v[180:183], v[80:95]
	v_mfma_f32_32x32x16_bf16 v[64:79], v[176:179], v[184:187], v[64:79]
	v_mfma_f32_32x32x16_bf16 v[16:31], v[176:179], v[188:191], v[16:31]
	v_mfma_f32_32x32x16_bf16 v[0:15], v[176:179], v[192:195], v[0:15]
	s_waitcnt vmcnt(8) lgkmcnt(0)
	s_barrier
	v_mfma_f32_32x32x16_bf16 v[112:127], v[212:215], v[220:223], v[112:127]
	ds_read_b128 v[172:175], v196 offset:32768
	s_mov_b32 m0, s5
	v_lshl_add_u64 v[142:143], v[136:137], 0, s[8:9]
	global_load_lds_dwordx4 v[142:143], off
	v_mfma_f32_32x32x16_bf16 v[96:111], v[212:215], v[224:227], v[96:111]
	ds_read_b128 v[176:179], v196 offset:34816
	s_add_u32 m0, s5, 0x2000
	v_lshl_add_u64 v[154:155], v[130:131], 0, s[8:9]
	global_load_lds_dwordx4 v[154:155], off
	v_mfma_f32_32x32x16_bf16 v[48:63], v[212:215], v[228:231], v[48:63]
	ds_read_b128 v[180:183], v197 offset:49152
	s_add_u32 m0, s5, 0x4000
	v_lshl_add_u64 v[142:143], v[140:141], 0, s[8:9]
	global_load_lds_dwordx4 v[142:143], off
	v_mfma_f32_32x32x16_bf16 v[32:47], v[212:215], v[232:235], v[32:47]
	ds_read_b128 v[184:187], v197 offset:51200
	s_add_u32 m0, s5, 0x6000
	v_lshl_add_u64 v[154:155], v[138:139], 0, s[8:9]
	global_load_lds_dwordx4 v[154:155], off
	ds_read_b128 v[212:215], v152 offset:32768
	s_add_u32 s8, s8, 64
	s_addc_u32 s9, s9, 0
	v_mfma_f32_32x32x16_bf16 v[80:95], v[216:219], v[220:223], v[80:95]
	ds_read_b128 v[188:191], v197 offset:53248
	ds_read_b128 v[220:223], v171 offset:49152
	v_mfma_f32_32x32x16_bf16 v[64:79], v[216:219], v[224:227], v[64:79]
	ds_read_b128 v[192:195], v197 offset:55296
	ds_read_b128 v[224:227], v171 offset:51200
	v_mfma_f32_32x32x16_bf16 v[16:31], v[216:219], v[228:231], v[16:31]
	ds_read_b128 v[228:231], v171 offset:53248
	v_mfma_f32_32x32x16_bf16 v[0:15], v[216:219], v[232:235], v[0:15]
	ds_read_b128 v[232:235], v171 offset:55296
	ds_read_b128 v[216:219], v152 offset:34816
	v_xor_b32_e32 v196, 0x10000, v196
	v_xor_b32_e32 v197, 0x10000, v197
	v_xor_b32_e32 v152, 0x10000, v152
	v_xor_b32_e32 v171, 0x10000, v171
	s_waitcnt lgkmcnt(4)
	v_mfma_f32_32x32x16_bf16 v[112:127], v[172:175], v[180:183], v[112:127]
	v_mfma_f32_32x32x16_bf16 v[96:111], v[172:175], v[184:187], v[96:111]
	v_mfma_f32_32x32x16_bf16 v[48:63], v[172:175], v[188:191], v[48:63]
	v_mfma_f32_32x32x16_bf16 v[32:47], v[172:175], v[192:195], v[32:47]
	v_mfma_f32_32x32x16_bf16 v[80:95], v[176:179], v[180:183], v[80:95]
	v_mfma_f32_32x32x16_bf16 v[64:79], v[176:179], v[184:187], v[64:79]
	v_mfma_f32_32x32x16_bf16 v[16:31], v[176:179], v[188:191], v[16:31]
	v_mfma_f32_32x32x16_bf16 v[0:15], v[176:179], v[192:195], v[0:15]
	s_waitcnt vmcnt(8) lgkmcnt(0)
	s_barrier
	v_mfma_f32_32x32x16_bf16 v[112:127], v[212:215], v[220:223], v[112:127]
	ds_read_b128 v[172:175], v196
	s_add_u32 m0, s5, 0x8000
	v_lshl_add_u64 v[142:143], v[136:137], 0, s[8:9]
	global_load_lds_dwordx4 v[142:143], off
	v_mfma_f32_32x32x16_bf16 v[96:111], v[212:215], v[224:227], v[96:111]
	ds_read_b128 v[176:179], v196 offset:2048
	s_add_u32 m0, s5, 0xa000
	v_lshl_add_u64 v[154:155], v[130:131], 0, s[8:9]
	global_load_lds_dwordx4 v[154:155], off
	v_mfma_f32_32x32x16_bf16 v[48:63], v[212:215], v[228:231], v[48:63]
	ds_read_b128 v[180:183], v197 offset:16384
	s_add_u32 m0, s5, 0xc000
	v_lshl_add_u64 v[142:143], v[140:141], 0, s[8:9]
	global_load_lds_dwordx4 v[142:143], off
	v_mfma_f32_32x32x16_bf16 v[32:47], v[212:215], v[232:235], v[32:47]
	ds_read_b128 v[184:187], v197 offset:18432
	s_add_u32 m0, s5, 0xe000
	v_lshl_add_u64 v[154:155], v[138:139], 0, s[8:9]
	global_load_lds_dwordx4 v[154:155], off
	ds_read_b128 v[212:215], v152
	s_add_u32 s8, s8, 64
	s_addc_u32 s9, s9, 0
	v_mfma_f32_32x32x16_bf16 v[80:95], v[216:219], v[220:223], v[80:95]
	ds_read_b128 v[188:191], v197 offset:20480
	ds_read_b128 v[220:223], v171 offset:16384
	v_mfma_f32_32x32x16_bf16 v[64:79], v[216:219], v[224:227], v[64:79]
	ds_read_b128 v[192:195], v197 offset:22528
	ds_read_b128 v[224:227], v171 offset:18432
	v_mfma_f32_32x32x16_bf16 v[16:31], v[216:219], v[228:231], v[16:31]
	ds_read_b128 v[228:231], v171 offset:20480
	v_mfma_f32_32x32x16_bf16 v[0:15], v[216:219], v[232:235], v[0:15]
	ds_read_b128 v[232:235], v171 offset:22528
	ds_read_b128 v[216:219], v152 offset:2048
	s_xor_b32 s5, s5, 0x10000
	s_add_u32 s0, s0, 0x80
	s_cmpk_lg_i32 s0, 0x1000
	s_cbranch_scc1 .Lgm_p1m_loop
	s_waitcnt lgkmcnt(0)
	s_mov_b64 s[8:9], 0xc0
	s_mov_b64 s[10:11], 0x100
	s_waitcnt vmcnt(0)
	s_waitcnt vmcnt(0)
	s_barrier
	s_and_saveexec_b64 s[0:1], vcc
	s_cbranch_execz .LBB0_929
	s_mov_b32 s4, 0x800000
	v_mul_f32_e32 v130, 0x4b800000, v135
	v_cmp_gt_f32_e32 vcc, s4, v135
	v_lshl_add_u32 v131, v128, 2, 0
	v_add_u32_e32 v131, 0x12000, v131
	v_cndmask_b32_e32 v130, v135, v130, vcc
	v_rsq_f32_e32 v130, v130
	s_nop 0
	v_mul_f32_e32 v135, 0x45800000, v130
	v_cndmask_b32_e32 v130, v130, v135, vcc
	ds_write_b32 v131, v130
